# phase-1 sample-row up-GEMM split along K over the waves, partial sums combined through LDS: 2.5x less L2 to CU traffic per workgroup
# speedup vs baseline: 1.0046x; 1.0028x over previous
; __device__ __forceinline__ int opq_tid() { int t = threadIdx.x; asm volatile("" : "+v"(t)); return t; }
; __device__ __forceinline__ int opq_bid() { int b = blockIdx.x; asm volatile("" : "+s"(b)); return b; }
; #define SK_LOAD(AR, BR, k0) do { _Pragma("unroll") for (int i = 0; i < UNR; ++i) { AR[i] = *(const bf16x8*)(ap + (k0) + 32 * i); \
;             _Pragma("unroll") for (int g = 0; g < NG; ++g) BR[g][i] = *(const bf16x8*)(bp[g] + (k0) + 32 * i); } } while (0)
; #define SK_MMA(AR, BR) do { _Pragma("unroll") for (int i = 0; i < UNR; ++i) _Pragma("unroll") for (int g = 0; g < NG; ++g) acc[g] = __builtin_amdgcn_mfma_f32_16x16x32_bf16(BR[g][i], AR[i], acc[g], 0, 0, 0); } while (0)
;     const int tid = opq_tid(), lane = tid & 63, w = tid >> 6, rr = lane & 15, kq = lane >> 4;
;     const int rg = KS == 2 ? (w & 3) : w, kh = KS == 2 ? (w >> 2) : 0, KL = K / KS;
;     for (int u = (opq_bid() + (int)gridDim.x - bshift) % (int)gridDim.x; u < 2 * KS * ngroups; u += gridDim.x) {
;         const int hv = u & (2 * KS - 1), cg = u / (2 * KS), srow = hv * (128 / KS) + rg * 16 + rr;
;         const bf16_t* ap = A + (size_t)srow * K + kh * KL + 8 * kq;
;         const bf16_t* bp[NG]; f32x4 acc[NG];
; #pragma unroll
;         for (int g = 0; g < NG; ++g) { bp[g] = Bt + (size_t)(Epi::brow(cg, g) + rr) * K + kh * KL + 8 * kq; acc[g] = (f32x4){0.f, 0.f, 0.f, 0.f}; }
;         bf16x8 a0[UNR], a1[UNR], b0[NG][UNR], b1[NG][UNR];
;     ...
;         SK_LOAD(a0, b0, 0);
;         for (int k = 0; k < KL; k += 64 * UNR) {
;             SK_LOAD(a1, b1, k + 32 * UNR);
;             SK_MMA(a0, b0);
;             if (k + 64 * UNR < KL) SK_LOAD(a0, b0, k + 64 * UNR);
;             SK_MMA(a1, b1);
;         }
.Lsku_beg:
	v_lshl_add_u64 v[72:73], v[62:63], 0, v[10:11]
	v_lshl_add_u64 v[70:71], v[62:63], 0, v[12:13]
	v_lshlrev_b64 v[24:25], 11, v[14:15]
	v_lshl_add_u64 v[74:75], v[62:63], 0, v[24:25]
	s_ashr_i32 s1, s0, 31
	s_add_i32 s3, s3, s6
	s_add_i32 s2, s2, s94
	s_cmpk_lt_i32 s2, 0xb0
	v_lshrrev_b32_e32 v228, 6, v254
	v_and_b32_e32 v229, 3, v228
	v_lshrrev_b32_e32 v230, 2, v228
	v_and_b32_e32 v231, 0x80, v32
	v_lshl_add_u32 v231, v230, 6, v231
	v_add_u32_e32 v231, v231, v78
	v_lshlrev_b32_e32 v232, 9, v229
	v_mov_b32_e32 v233, 0
	v_mov_b32_e32 v235, 0
	v_lshl_add_u64 v[68:69], v[68:69], 0, v[232:233]
	v_lshl_add_u64 v[72:73], v[72:73], 0, v[232:233]
	v_lshl_add_u64 v[70:71], v[70:71], 0, v[232:233]
	v_lshl_add_u64 v[74:75], v[74:75], 0, v[232:233]
	v_add_u32_e32 v234, 0, v231
	v_lshlrev_b32_e32 v234, 11, v234
	v_lshl_add_u64 v[220:221], v[234:235], 0, v[64:65]
	v_lshl_add_u64 v[220:221], v[220:221], 0, v[232:233]
	v_add_u32_e32 v234, 16, v231
	v_lshlrev_b32_e32 v234, 11, v234
	v_lshl_add_u64 v[222:223], v[234:235], 0, v[64:65]
	v_lshl_add_u64 v[222:223], v[222:223], 0, v[232:233]
	v_add_u32_e32 v234, 32, v231
	v_lshlrev_b32_e32 v234, 11, v234
	v_lshl_add_u64 v[224:225], v[234:235], 0, v[64:65]
	v_lshl_add_u64 v[224:225], v[224:225], 0, v[232:233]
	v_add_u32_e32 v234, 48, v231
	v_lshlrev_b32_e32 v234, 11, v234
	v_lshl_add_u64 v[226:227], v[234:235], 0, v[64:65]
	v_lshl_add_u64 v[226:227], v[226:227], 0, v[232:233]
	v_lshl_add_u32 v236, v229, 4, v231
	v_and_b32_e32 v244, 63, v254
	v_lshlrev_b32_e32 v244, 4, v244
	v_lshl_add_u32 v240, v228, 14, v244
	v_lshl_add_u32 v241, v230, 16, v244
	v_lshl_add_u32 v241, v229, 12, v241
	global_load_dwordx4 v[0:3], v[220:221], off
	global_load_dwordx4 v[4:7], v[222:223], off
	global_load_dwordx4 v[8:11], v[224:225], off
	global_load_dwordx4 v[12:15], v[226:227], off
	global_load_dwordx4 v[16:19], v[68:69], off
	global_load_dwordx4 v[20:23], v[72:73], off
	global_load_dwordx4 v[24:27], v[70:71], off
	global_load_dwordx4 v[28:31], v[74:75], off
	global_load_dwordx4 v[36:39], v[220:221], off offset:64
	global_load_dwordx4 v[40:43], v[222:223], off offset:64
	global_load_dwordx4 v[44:47], v[224:225], off offset:64
	global_load_dwordx4 v[48:51], v[226:227], off offset:64
	global_load_dwordx4 v[52:55], v[68:69], off offset:64
	global_load_dwordx4 v[56:59], v[72:73], off offset:64
	global_load_dwordx4 v[148:151], v[70:71], off offset:64
	global_load_dwordx4 v[152:155], v[74:75], off offset:64
	global_load_dwordx4 v[156:159], v[220:221], off offset:128
	global_load_dwordx4 v[160:163], v[222:223], off offset:128
	global_load_dwordx4 v[164:167], v[224:225], off offset:128
	global_load_dwordx4 v[168:171], v[226:227], off offset:128
	global_load_dwordx4 v[172:175], v[68:69], off offset:128
	global_load_dwordx4 v[176:179], v[72:73], off offset:128
	global_load_dwordx4 v[180:183], v[70:71], off offset:128
	global_load_dwordx4 v[184:187], v[74:75], off offset:128
	global_load_dwordx4 v[188:191], v[220:221], off offset:192
	global_load_dwordx4 v[192:195], v[222:223], off offset:192
	global_load_dwordx4 v[196:199], v[224:225], off offset:192
	global_load_dwordx4 v[200:203], v[226:227], off offset:192
	global_load_dwordx4 v[204:207], v[68:69], off offset:192
	global_load_dwordx4 v[208:211], v[72:73], off offset:192
	global_load_dwordx4 v[212:215], v[70:71], off offset:192
	global_load_dwordx4 v[216:219], v[74:75], off offset:192
	s_waitcnt vmcnt(24)
	v_mfma_f32_16x16x32_bf16 v[84:87], v[16:19], v[0:3], 0
	v_mfma_f32_16x16x32_bf16 v[88:91], v[20:23], v[0:3], 0
	v_mfma_f32_16x16x32_bf16 v[92:95], v[24:27], v[0:3], 0
	v_mfma_f32_16x16x32_bf16 v[96:99], v[28:31], v[0:3], 0
	v_mfma_f32_16x16x32_bf16 v[100:103], v[16:19], v[4:7], 0
	v_mfma_f32_16x16x32_bf16 v[104:107], v[20:23], v[4:7], 0
	v_mfma_f32_16x16x32_bf16 v[108:111], v[24:27], v[4:7], 0
	v_mfma_f32_16x16x32_bf16 v[112:115], v[28:31], v[4:7], 0
	v_mfma_f32_16x16x32_bf16 v[116:119], v[16:19], v[8:11], 0
	v_mfma_f32_16x16x32_bf16 v[120:123], v[20:23], v[8:11], 0
	v_mfma_f32_16x16x32_bf16 v[124:127], v[24:27], v[8:11], 0
	v_mfma_f32_16x16x32_bf16 v[128:131], v[28:31], v[8:11], 0
	v_mfma_f32_16x16x32_bf16 v[132:135], v[16:19], v[12:15], 0
	v_mfma_f32_16x16x32_bf16 v[136:139], v[20:23], v[12:15], 0
	v_mfma_f32_16x16x32_bf16 v[140:143], v[24:27], v[12:15], 0
	v_mfma_f32_16x16x32_bf16 v[144:147], v[28:31], v[12:15], 0
	global_load_dwordx4 v[0:3], v[220:221], off offset:256
	global_load_dwordx4 v[4:7], v[222:223], off offset:256
	global_load_dwordx4 v[8:11], v[224:225], off offset:256
	global_load_dwordx4 v[12:15], v[226:227], off offset:256
	global_load_dwordx4 v[16:19], v[68:69], off offset:256
	global_load_dwordx4 v[20:23], v[72:73], off offset:256
	global_load_dwordx4 v[24:27], v[70:71], off offset:256
	global_load_dwordx4 v[28:31], v[74:75], off offset:256
	s_waitcnt vmcnt(24)
	v_mfma_f32_16x16x32_bf16 v[84:87], v[52:55], v[36:39], v[84:87]
	v_mfma_f32_16x16x32_bf16 v[88:91], v[56:59], v[36:39], v[88:91]
	v_mfma_f32_16x16x32_bf16 v[92:95], v[148:151], v[36:39], v[92:95]
	v_mfma_f32_16x16x32_bf16 v[96:99], v[152:155], v[36:39], v[96:99]
	v_mfma_f32_16x16x32_bf16 v[100:103], v[52:55], v[40:43], v[100:103]
	v_mfma_f32_16x16x32_bf16 v[104:107], v[56:59], v[40:43], v[104:107]
	v_mfma_f32_16x16x32_bf16 v[108:111], v[148:151], v[40:43], v[108:111]
	v_mfma_f32_16x16x32_bf16 v[112:115], v[152:155], v[40:43], v[112:115]
	v_mfma_f32_16x16x32_bf16 v[116:119], v[52:55], v[44:47], v[116:119]
	v_mfma_f32_16x16x32_bf16 v[120:123], v[56:59], v[44:47], v[120:123]
	v_mfma_f32_16x16x32_bf16 v[124:127], v[148:151], v[44:47], v[124:127]
	v_mfma_f32_16x16x32_bf16 v[128:131], v[152:155], v[44:47], v[128:131]
	v_mfma_f32_16x16x32_bf16 v[132:135], v[52:55], v[48:51], v[132:135]
	v_mfma_f32_16x16x32_bf16 v[136:139], v[56:59], v[48:51], v[136:139]
	v_mfma_f32_16x16x32_bf16 v[140:143], v[148:151], v[48:51], v[140:143]
	v_mfma_f32_16x16x32_bf16 v[144:147], v[152:155], v[48:51], v[144:147]
	global_load_dwordx4 v[36:39], v[220:221], off offset:320
	global_load_dwordx4 v[40:43], v[222:223], off offset:320
	global_load_dwordx4 v[44:47], v[224:225], off offset:320
	global_load_dwordx4 v[48:51], v[226:227], off offset:320
	global_load_dwordx4 v[52:55], v[68:69], off offset:320
	global_load_dwordx4 v[56:59], v[72:73], off offset:320
	global_load_dwordx4 v[148:151], v[70:71], off offset:320
	global_load_dwordx4 v[152:155], v[74:75], off offset:320
	s_waitcnt vmcnt(24)
; #define SK_LOAD(AR, BR, k0) do { _Pragma("unroll") for (int i = 0; i < UNR; ++i) { AR[i] = *(const bf16x8*)(ap + (k0) + 32 * i); \
;             _Pragma("unroll") for (int g = 0; g < NG; ++g) BR[g][i] = *(const bf16x8*)(bp[g] + (k0) + 32 * i); } } while (0)
; #define SK_MMA(AR, BR) do { _Pragma("unroll") for (int i = 0; i < UNR; ++i) _Pragma("unroll") for (int g = 0; g < NG; ++g) acc[g] = __builtin_amdgcn_mfma_f32_16x16x32_bf16(BR[g][i], AR[i], acc[g], 0, 0, 0); } while (0)
;     ...
;         SK_LOAD(a0, b0, 0);
;         for (int k = 0; k < KL; k += 64 * UNR) {
;             SK_LOAD(a1, b1, k + 32 * UNR);
;             SK_MMA(a0, b0);
;             if (k + 64 * UNR < KL) SK_LOAD(a0, b0, k + 64 * UNR);
;             SK_MMA(a1, b1);
;         }
	v_mfma_f32_16x16x32_bf16 v[84:87], v[172:175], v[156:159], v[84:87]
	v_mfma_f32_16x16x32_bf16 v[88:91], v[176:179], v[156:159], v[88:91]
	v_mfma_f32_16x16x32_bf16 v[92:95], v[180:183], v[156:159], v[92:95]
	v_mfma_f32_16x16x32_bf16 v[96:99], v[184:187], v[156:159], v[96:99]
	v_mfma_f32_16x16x32_bf16 v[100:103], v[172:175], v[160:163], v[100:103]
	v_mfma_f32_16x16x32_bf16 v[104:107], v[176:179], v[160:163], v[104:107]
	v_mfma_f32_16x16x32_bf16 v[108:111], v[180:183], v[160:163], v[108:111]
	v_mfma_f32_16x16x32_bf16 v[112:115], v[184:187], v[160:163], v[112:115]
	v_mfma_f32_16x16x32_bf16 v[116:119], v[172:175], v[164:167], v[116:119]
	v_mfma_f32_16x16x32_bf16 v[120:123], v[176:179], v[164:167], v[120:123]
	v_mfma_f32_16x16x32_bf16 v[124:127], v[180:183], v[164:167], v[124:127]
	v_mfma_f32_16x16x32_bf16 v[128:131], v[184:187], v[164:167], v[128:131]
	v_mfma_f32_16x16x32_bf16 v[132:135], v[172:175], v[168:171], v[132:135]
	v_mfma_f32_16x16x32_bf16 v[136:139], v[176:179], v[168:171], v[136:139]
	v_mfma_f32_16x16x32_bf16 v[140:143], v[180:183], v[168:171], v[140:143]
	v_mfma_f32_16x16x32_bf16 v[144:147], v[184:187], v[168:171], v[144:147]
	global_load_dwordx4 v[156:159], v[220:221], off offset:384
	global_load_dwordx4 v[160:163], v[222:223], off offset:384
	global_load_dwordx4 v[164:167], v[224:225], off offset:384
	global_load_dwordx4 v[168:171], v[226:227], off offset:384
	global_load_dwordx4 v[172:175], v[68:69], off offset:384
	global_load_dwordx4 v[176:179], v[72:73], off offset:384
	global_load_dwordx4 v[180:183], v[70:71], off offset:384
	global_load_dwordx4 v[184:187], v[74:75], off offset:384
	s_waitcnt vmcnt(24)
	v_mfma_f32_16x16x32_bf16 v[84:87], v[204:207], v[188:191], v[84:87]
	v_mfma_f32_16x16x32_bf16 v[88:91], v[208:211], v[188:191], v[88:91]
	v_mfma_f32_16x16x32_bf16 v[92:95], v[212:215], v[188:191], v[92:95]
	v_mfma_f32_16x16x32_bf16 v[96:99], v[216:219], v[188:191], v[96:99]
	v_mfma_f32_16x16x32_bf16 v[100:103], v[204:207], v[192:195], v[100:103]
	v_mfma_f32_16x16x32_bf16 v[104:107], v[208:211], v[192:195], v[104:107]
	v_mfma_f32_16x16x32_bf16 v[108:111], v[212:215], v[192:195], v[108:111]
	v_mfma_f32_16x16x32_bf16 v[112:115], v[216:219], v[192:195], v[112:115]
	v_mfma_f32_16x16x32_bf16 v[116:119], v[204:207], v[196:199], v[116:119]
	v_mfma_f32_16x16x32_bf16 v[120:123], v[208:211], v[196:199], v[120:123]
	v_mfma_f32_16x16x32_bf16 v[124:127], v[212:215], v[196:199], v[124:127]
	v_mfma_f32_16x16x32_bf16 v[128:131], v[216:219], v[196:199], v[128:131]
	v_mfma_f32_16x16x32_bf16 v[132:135], v[204:207], v[200:203], v[132:135]
	v_mfma_f32_16x16x32_bf16 v[136:139], v[208:211], v[200:203], v[136:139]
	v_mfma_f32_16x16x32_bf16 v[140:143], v[212:215], v[200:203], v[140:143]
	v_mfma_f32_16x16x32_bf16 v[144:147], v[216:219], v[200:203], v[144:147]
	global_load_dwordx4 v[188:191], v[220:221], off offset:448
	global_load_dwordx4 v[192:195], v[222:223], off offset:448
	global_load_dwordx4 v[196:199], v[224:225], off offset:448
	global_load_dwordx4 v[200:203], v[226:227], off offset:448
	global_load_dwordx4 v[204:207], v[68:69], off offset:448
	global_load_dwordx4 v[208:211], v[72:73], off offset:448
	global_load_dwordx4 v[212:215], v[70:71], off offset:448
	global_load_dwordx4 v[216:219], v[74:75], off offset:448
	s_waitcnt vmcnt(24)
	v_mfma_f32_16x16x32_bf16 v[84:87], v[16:19], v[0:3], v[84:87]
	v_mfma_f32_16x16x32_bf16 v[88:91], v[20:23], v[0:3], v[88:91]
	v_mfma_f32_16x16x32_bf16 v[92:95], v[24:27], v[0:3], v[92:95]
	v_mfma_f32_16x16x32_bf16 v[96:99], v[28:31], v[0:3], v[96:99]
	v_mfma_f32_16x16x32_bf16 v[100:103], v[16:19], v[4:7], v[100:103]
	v_mfma_f32_16x16x32_bf16 v[104:107], v[20:23], v[4:7], v[104:107]
	v_mfma_f32_16x16x32_bf16 v[108:111], v[24:27], v[4:7], v[108:111]
	v_mfma_f32_16x16x32_bf16 v[112:115], v[28:31], v[4:7], v[112:115]
	v_mfma_f32_16x16x32_bf16 v[116:119], v[16:19], v[8:11], v[116:119]
	v_mfma_f32_16x16x32_bf16 v[120:123], v[20:23], v[8:11], v[120:123]
	v_mfma_f32_16x16x32_bf16 v[124:127], v[24:27], v[8:11], v[124:127]
	v_mfma_f32_16x16x32_bf16 v[128:131], v[28:31], v[8:11], v[128:131]
	v_mfma_f32_16x16x32_bf16 v[132:135], v[16:19], v[12:15], v[132:135]
	v_mfma_f32_16x16x32_bf16 v[136:139], v[20:23], v[12:15], v[136:139]
	v_mfma_f32_16x16x32_bf16 v[140:143], v[24:27], v[12:15], v[140:143]
	v_mfma_f32_16x16x32_bf16 v[144:147], v[28:31], v[12:15], v[144:147]
	s_waitcnt vmcnt(16)
	v_mfma_f32_16x16x32_bf16 v[84:87], v[52:55], v[36:39], v[84:87]
	v_mfma_f32_16x16x32_bf16 v[88:91], v[56:59], v[36:39], v[88:91]
	v_mfma_f32_16x16x32_bf16 v[92:95], v[148:151], v[36:39], v[92:95]
	v_mfma_f32_16x16x32_bf16 v[96:99], v[152:155], v[36:39], v[96:99]
	v_mfma_f32_16x16x32_bf16 v[100:103], v[52:55], v[40:43], v[100:103]
	v_mfma_f32_16x16x32_bf16 v[104:107], v[56:59], v[40:43], v[104:107]
	v_mfma_f32_16x16x32_bf16 v[108:111], v[148:151], v[40:43], v[108:111]
	v_mfma_f32_16x16x32_bf16 v[112:115], v[152:155], v[40:43], v[112:115]
	v_mfma_f32_16x16x32_bf16 v[116:119], v[52:55], v[44:47], v[116:119]
	v_mfma_f32_16x16x32_bf16 v[120:123], v[56:59], v[44:47], v[120:123]
	v_mfma_f32_16x16x32_bf16 v[124:127], v[148:151], v[44:47], v[124:127]
	v_mfma_f32_16x16x32_bf16 v[128:131], v[152:155], v[44:47], v[128:131]
	v_mfma_f32_16x16x32_bf16 v[132:135], v[52:55], v[48:51], v[132:135]
	v_mfma_f32_16x16x32_bf16 v[136:139], v[56:59], v[48:51], v[136:139]
	v_mfma_f32_16x16x32_bf16 v[140:143], v[148:151], v[48:51], v[140:143]
	v_mfma_f32_16x16x32_bf16 v[144:147], v[152:155], v[48:51], v[144:147]
	s_waitcnt vmcnt(8)
; #define LAS __attribute__((address_space(3)))
;     ...
;         if constexpr (KS == 2) {
;             LAS f32x4* xch = (LAS f32x4*)lds;
;             if (kh == 1) xch[rg * 64 + lane] = acc[0] + (f32x4){0.f, 0.f, 0.f, 0.f};
;             __syncthreads();
;             if (kh == 0) { acc[0] += xch[rg * 64 + lane]; E(acc, srow, cg, kq); }
;             __syncthreads();
;         } else E(acc, srow, cg, kq);
; __device__ __forceinline__ float rs_sample(const float* ssps, int srow) { return rs_from(ssps + (size_t)srow * 64, 16, 1.0f / 1024.0f); }
	v_mfma_f32_16x16x32_bf16 v[84:87], v[172:175], v[156:159], v[84:87]
	v_mfma_f32_16x16x32_bf16 v[88:91], v[176:179], v[156:159], v[88:91]
	v_mfma_f32_16x16x32_bf16 v[92:95], v[180:183], v[156:159], v[92:95]
	v_mfma_f32_16x16x32_bf16 v[96:99], v[184:187], v[156:159], v[96:99]
	v_mfma_f32_16x16x32_bf16 v[100:103], v[172:175], v[160:163], v[100:103]
	v_mfma_f32_16x16x32_bf16 v[104:107], v[176:179], v[160:163], v[104:107]
	v_mfma_f32_16x16x32_bf16 v[108:111], v[180:183], v[160:163], v[108:111]
	v_mfma_f32_16x16x32_bf16 v[112:115], v[184:187], v[160:163], v[112:115]
	v_mfma_f32_16x16x32_bf16 v[116:119], v[172:175], v[164:167], v[116:119]
	v_mfma_f32_16x16x32_bf16 v[120:123], v[176:179], v[164:167], v[120:123]
	v_mfma_f32_16x16x32_bf16 v[124:127], v[180:183], v[164:167], v[124:127]
	v_mfma_f32_16x16x32_bf16 v[128:131], v[184:187], v[164:167], v[128:131]
	v_mfma_f32_16x16x32_bf16 v[132:135], v[172:175], v[168:171], v[132:135]
	v_mfma_f32_16x16x32_bf16 v[136:139], v[176:179], v[168:171], v[136:139]
	v_mfma_f32_16x16x32_bf16 v[140:143], v[180:183], v[168:171], v[140:143]
	v_mfma_f32_16x16x32_bf16 v[144:147], v[184:187], v[168:171], v[144:147]
	s_waitcnt vmcnt(0)
	v_mfma_f32_16x16x32_bf16 v[84:87], v[204:207], v[188:191], v[84:87]
	v_mfma_f32_16x16x32_bf16 v[88:91], v[208:211], v[188:191], v[88:91]
	v_mfma_f32_16x16x32_bf16 v[92:95], v[212:215], v[188:191], v[92:95]
	v_mfma_f32_16x16x32_bf16 v[96:99], v[216:219], v[188:191], v[96:99]
	v_mfma_f32_16x16x32_bf16 v[100:103], v[204:207], v[192:195], v[100:103]
	v_mfma_f32_16x16x32_bf16 v[104:107], v[208:211], v[192:195], v[104:107]
	v_mfma_f32_16x16x32_bf16 v[108:111], v[212:215], v[192:195], v[108:111]
	v_mfma_f32_16x16x32_bf16 v[112:115], v[216:219], v[192:195], v[112:115]
	v_mfma_f32_16x16x32_bf16 v[116:119], v[204:207], v[196:199], v[116:119]
	v_mfma_f32_16x16x32_bf16 v[120:123], v[208:211], v[196:199], v[120:123]
	v_mfma_f32_16x16x32_bf16 v[124:127], v[212:215], v[196:199], v[124:127]
	v_mfma_f32_16x16x32_bf16 v[128:131], v[216:219], v[196:199], v[128:131]
	v_mfma_f32_16x16x32_bf16 v[132:135], v[204:207], v[200:203], v[132:135]
	v_mfma_f32_16x16x32_bf16 v[136:139], v[208:211], v[200:203], v[136:139]
	v_mfma_f32_16x16x32_bf16 v[140:143], v[212:215], v[200:203], v[140:143]
	v_mfma_f32_16x16x32_bf16 v[144:147], v[216:219], v[200:203], v[144:147]
	v_lshlrev_b32_e32 v234, 8, v236
	v_lshl_add_u64 v[238:239], v[234:235], 0, s[92:93]
	v_lshl_add_u64 v[238:239], v[60:61], 3, v[238:239]
	global_load_dwordx4 v[0:3], v[238:239], off
	global_load_dwordx4 v[4:7], v[238:239], off offset:16
	global_load_dwordx4 v[8:11], v[238:239], off offset:32
	global_load_dwordx4 v[12:15], v[238:239], off offset:48
	s_nop 7
	ds_write_b128 v240, v[84:87] offset:0
	ds_write_b128 v240, v[88:91] offset:1024
	ds_write_b128 v240, v[92:95] offset:2048
	ds_write_b128 v240, v[96:99] offset:3072
	ds_write_b128 v240, v[100:103] offset:4096
	ds_write_b128 v240, v[104:107] offset:5120
	ds_write_b128 v240, v[108:111] offset:6144
	ds_write_b128 v240, v[112:115] offset:7168
	ds_write_b128 v240, v[116:119] offset:8192
	ds_write_b128 v240, v[120:123] offset:9216
	ds_write_b128 v240, v[124:127] offset:10240
	ds_write_b128 v240, v[128:131] offset:11264
	ds_write_b128 v240, v[132:135] offset:12288
	ds_write_b128 v240, v[136:139] offset:13312
	ds_write_b128 v240, v[140:143] offset:14336
	ds_write_b128 v240, v[144:147] offset:15360
	s_waitcnt lgkmcnt(0)
	s_barrier
	ds_read_b128 v[148:151], v241 offset:0
	ds_read_b128 v[152:155], v241 offset:16384
	ds_read_b128 v[156:159], v241 offset:32768
	ds_read_b128 v[160:163], v241 offset:49152
	ds_read_b128 v[164:167], v241 offset:1024
	ds_read_b128 v[168:171], v241 offset:17408
	ds_read_b128 v[172:175], v241 offset:33792
	ds_read_b128 v[176:179], v241 offset:50176
	ds_read_b128 v[180:183], v241 offset:2048
	ds_read_b128 v[184:187], v241 offset:18432
	ds_read_b128 v[188:191], v241 offset:34816
	ds_read_b128 v[192:195], v241 offset:51200
	ds_read_b128 v[196:199], v241 offset:3072
	ds_read_b128 v[200:203], v241 offset:19456
	ds_read_b128 v[204:207], v241 offset:35840
	ds_read_b128 v[208:211], v241 offset:52224
	v_add_u32_e32 v244, 0x8000, v236
	v_mad_i64_i32 v[242:243], s[10:11], v244, s8, v[66:67]
	v_lshl_add_u64 v[242:243], s[0:1], 1, v[242:243]
	v_lshl_add_u64 v[242:243], v[242:243], 0, v[60:61]
	v_mbcnt_lo_u32_b32 v245, -1, 0
	v_mbcnt_hi_u32_b32 v245, -1, v245
	v_xor_b32_e32 v246, 16, v245
	v_xor_b32_e32 v247, 32, v245
	v_lshlrev_b32_e32 v246, 2, v246
	v_lshlrev_b32_e32 v247, 2, v247
	s_waitcnt lgkmcnt(0)
	s_barrier
; __device__ __forceinline__ unsigned cvt_pk_bf16(float lo, float hi) { unsigned r; asm volatile("v_cvt_pk_bf16_f32 %0, %1, %2" : "=v"(r) : "v"(lo), "v"(hi)); return r; }
; __device__ __forceinline__ float rs_sample(const float* ssps, int srow) { return rs_from(ssps + (size_t)srow * 64, 16, 1.0f / 1024.0f); }
;     __device__ __forceinline__ void operator()(const f32x4 (&acc)[2], int srow, int cgp, int kq) const { one(acc[0], srow, 2 * cgp, kq); one(acc[1], srow, 2 * cgp + 1, kq); }
; __device__ __forceinline__ float rs_from(const float* p, int n4, float inv_n) {
;     float s = 0.f;
;     for (int i = 0; i < n4; ++i) { const f32x4 v = *(const f32x4*)(p + 4 * i); s += (v[0] + v[1]) + (v[2] + v[3]); }
;     return rsqrtf(s * inv_n + EPS);
; }
;     __device__ __forceinline__ void operator()(const f32x4 (&acc)[4], int srow, int cgp, int kq) const {
;         const float rs = rs_sample(ssps, srow);
; #pragma unroll
;         for (int q = 0; q < 2; ++q) { f32x4 o;
; #pragma unroll
;             for (int j = 0; j < 4; ++j) { const float g = acc[2 * q][j] * rs, up = acc[2 * q + 1][j] * rs; o[j] = g * __builtin_amdgcn_rcpf(1.0f + __expf(-g)) * up; }
;             u32x2 w; w.x = cvt_pk_bf16(o[0], o[1]); w.y = cvt_pk_bf16(o[2], o[3]);
;             *(u32x2*)(act + (size_t)(TP + srow) * FF + (2 * cgp + q) * 16 + 4 * kq) = w; }
;     }
	v_add_f32_e32 v84, v148, v152
	v_add_f32_e32 v85, v149, v153
	v_add_f32_e32 v86, v150, v154
	v_add_f32_e32 v87, v151, v155
	v_add_f32_e32 v84, v84, v156
	v_add_f32_e32 v85, v85, v157
	v_add_f32_e32 v86, v86, v158
	v_add_f32_e32 v87, v87, v159
	v_add_f32_e32 v84, v84, v160
	v_add_f32_e32 v85, v85, v161
	v_add_f32_e32 v86, v86, v162
	v_add_f32_e32 v87, v87, v163
	v_add_f32_e32 v88, v164, v168
	v_add_f32_e32 v89, v165, v169
	v_add_f32_e32 v90, v166, v170
	v_add_f32_e32 v91, v167, v171
	v_add_f32_e32 v88, v88, v172
	v_add_f32_e32 v89, v89, v173
	v_add_f32_e32 v90, v90, v174
	v_add_f32_e32 v91, v91, v175
	v_add_f32_e32 v88, v88, v176
	v_add_f32_e32 v89, v89, v177
	v_add_f32_e32 v90, v90, v178
	v_add_f32_e32 v91, v91, v179
	v_add_f32_e32 v92, v180, v184
	v_add_f32_e32 v93, v181, v185
	v_add_f32_e32 v94, v182, v186
	v_add_f32_e32 v95, v183, v187
	v_add_f32_e32 v92, v92, v188
	v_add_f32_e32 v93, v93, v189
	v_add_f32_e32 v94, v94, v190
	v_add_f32_e32 v95, v95, v191
	v_add_f32_e32 v92, v92, v192
	v_add_f32_e32 v93, v93, v193
	v_add_f32_e32 v94, v94, v194
	v_add_f32_e32 v95, v95, v195
	v_add_f32_e32 v96, v196, v200
	v_add_f32_e32 v97, v197, v201
	v_add_f32_e32 v98, v198, v202
	v_add_f32_e32 v99, v199, v203
	v_add_f32_e32 v96, v96, v204
	v_add_f32_e32 v97, v97, v205
	v_add_f32_e32 v98, v98, v206
	v_add_f32_e32 v99, v99, v207
	v_add_f32_e32 v96, v96, v208
	v_add_f32_e32 v97, v97, v209
	v_add_f32_e32 v98, v98, v210
	v_add_f32_e32 v99, v99, v211
	s_waitcnt vmcnt(0)
	v_add_f32_e32 v0, v0, v1
	v_add_f32_e32 v2, v2, v3
	v_add_f32_e32 v0, v0, v2
	v_add_f32_e32 v4, v4, v5
	v_add_f32_e32 v6, v6, v7
	v_add_f32_e32 v4, v4, v6
	v_add_f32_e32 v8, v8, v9
	v_add_f32_e32 v10, v10, v11
	v_add_f32_e32 v8, v8, v10
	v_add_f32_e32 v12, v12, v13
	v_add_f32_e32 v14, v14, v15
	v_add_f32_e32 v12, v12, v14
	v_add_f32_e32 v0, v0, v4
	v_add_f32_e32 v8, v8, v12
	v_add_f32_e32 v0, v0, v8
	ds_bpermute_b32 v1, v246, v0
	s_waitcnt lgkmcnt(0)
	v_add_f32_e32 v0, v0, v1
	ds_bpermute_b32 v1, v247, v0
	s_waitcnt lgkmcnt(0)
	v_add_f32_e32 v0, v0, v1
	v_fmamk_f32 v0, v0, 0x3a800000, v80
	v_rsq_f32_e32 v0, v0
	s_nop 0
	v_pk_mul_f32 v[84:85], v[84:85], v[0:1] op_sel_hi:[1,0]
	v_pk_mul_f32 v[86:87], v[86:87], v[0:1] op_sel_hi:[1,0]
	v_pk_mul_f32 v[88:89], v[88:89], v[0:1] op_sel_hi:[1,0]
	v_pk_mul_f32 v[90:91], v[90:91], v[0:1] op_sel_hi:[1,0]
	v_pk_mul_f32 v[92:93], v[92:93], v[0:1] op_sel_hi:[1,0]
	v_pk_mul_f32 v[94:95], v[94:95], v[0:1] op_sel_hi:[1,0]
	v_pk_mul_f32 v[96:97], v[96:97], v[0:1] op_sel_hi:[1,0]
	v_pk_mul_f32 v[98:99], v[98:99], v[0:1] op_sel_hi:[1,0]
	v_mul_f32_e32 v16, 0xbfb8aa3b, v84
	v_mul_f32_e32 v17, 0xbfb8aa3b, v85
	v_mul_f32_e32 v18, 0xbfb8aa3b, v86
	v_mul_f32_e32 v19, 0xbfb8aa3b, v87
	v_mul_f32_e32 v20, 0xbfb8aa3b, v92
	v_mul_f32_e32 v21, 0xbfb8aa3b, v93
	v_mul_f32_e32 v22, 0xbfb8aa3b, v94
	v_mul_f32_e32 v23, 0xbfb8aa3b, v95
	v_exp_f32_e32 v16, v16
	v_exp_f32_e32 v17, v17
	v_exp_f32_e32 v18, v18
	v_exp_f32_e32 v19, v19
	v_exp_f32_e32 v20, v20
	v_exp_f32_e32 v21, v21
	v_exp_f32_e32 v22, v22
	v_exp_f32_e32 v23, v23
	v_add_f32_e32 v16, 1.0, v16
	v_add_f32_e32 v17, 1.0, v17
	v_add_f32_e32 v18, 1.0, v18
	v_add_f32_e32 v19, 1.0, v19
	v_add_f32_e32 v20, 1.0, v20
	v_add_f32_e32 v21, 1.0, v21
	v_add_f32_e32 v22, 1.0, v22
	v_add_f32_e32 v23, 1.0, v23
	v_rcp_f32_e32 v16, v16
	v_rcp_f32_e32 v17, v17
	v_rcp_f32_e32 v18, v18
	v_rcp_f32_e32 v19, v19
	v_rcp_f32_e32 v20, v20
	v_rcp_f32_e32 v21, v21
	v_rcp_f32_e32 v22, v22
	v_rcp_f32_e32 v23, v23
	v_mul_f32_e32 v16, v84, v16
	v_mul_f32_e32 v17, v85, v17
	v_mul_f32_e32 v18, v86, v18
	v_mul_f32_e32 v19, v87, v19
	v_mul_f32_e32 v20, v92, v20
	v_mul_f32_e32 v21, v93, v21
	v_mul_f32_e32 v22, v94, v22
	v_mul_f32_e32 v23, v95, v23
	v_mul_f32_e32 v16, v88, v16
	v_mul_f32_e32 v17, v89, v17
	v_mul_f32_e32 v18, v90, v18
	v_mul_f32_e32 v19, v91, v19
	v_mul_f32_e32 v20, v96, v20
	v_mul_f32_e32 v21, v97, v21
	v_mul_f32_e32 v22, v98, v22
	v_mul_f32_e32 v23, v99, v23
	v_cvt_pk_bf16_f32 v24, v16, v17
	v_cvt_pk_bf16_f32 v25, v18, v19
	v_cvt_pk_bf16_f32 v26, v20, v21
	v_cvt_pk_bf16_f32 v27, v22, v23
	global_store_dwordx2 v[242:243], v[24:25], off
	global_store_dwordx2 v[242:243], v[26:27], off offset:32

;     __device__ __forceinline__ void operator()(const f32x4 (&acc)[2], int srow, int cgp, int kq) const { one(acc[0], srow, 2 * cgp, kq); one(acc[1], srow, 2 * cgp + 1, kq); }
;     __device__ __forceinline__ void operator()(AccRef acc, const pg8::Unit& u, int wr, int wc, int fr, int fq) const {
;         const int row0 = u.pm * 256 + wr * 64 + fr, col0 = u.pn * 128 + wc * 32 + 8 * fq;
; #pragma unroll
;         for (int ai = 0; ai < 2; ++ai)
; #pragma unroll
;             for (int m = 0; m < 4; ++m) {
;                 const int row = row0 + ai * 128 + m * 16;
;                 const float rs = rs_from(ssp + (size_t)row * 16, 4, 1.0f / 1024.0f);
;                 f32x4 o[2];
; #pragma unroll
;                 for (int n = 0; n < 2; ++n)
; #pragma unroll
;                     for (int j = 0; j < 4; ++j) {
;                         const float g = acc[ai][0][m][n][j] * rs, up = acc[ai][1][m][n][j] * rs;
;                         o[n][j] = g * __builtin_amdgcn_rcpf(1.0f + __expf(-g)) * up;
;                     }
;                 *(u32x4*)(act + (size_t)row * FF + col0) = pack8(o[0], o[1]);
;             }
.LBB0_376:
.Lswi_beg0:
	v_add_u32_e32 v249, 0x2000, v247
	global_load_dwordx4 v[154:157], v249, s[46:47]
	global_load_dwordx4 v[158:161], v249, s[46:47] offset:1024
	global_load_dwordx4 v[162:165], v249, s[46:47] offset:2048
	global_load_dwordx4 v[166:169], v249, s[46:47] offset:3072
	v_mbcnt_lo_u32_b32 v170, -1, 0
	v_mbcnt_hi_u32_b32 v170, -1, v170
	v_xor_b32_e32 v171, 16, v170
	v_xor_b32_e32 v172, 32, v170
	v_lshlrev_b32_e32 v171, 2, v171
	v_lshlrev_b32_e32 v172, 2, v172
	v_lshl_or_b32 v173, s61, 7, v148
	v_lshlrev_b32_e32 v173, 1, v173
	v_mad_u32_u24 v248, v246, s51, v173
	s_waitcnt vmcnt(12)
	v_add_f32_e32 v230, v230, v231
	v_add_f32_e32 v232, v232, v233
	v_add_f32_e32 v234, v234, v235
	v_add_f32_e32 v236, v236, v237
	v_add_f32_e32 v238, v238, v239
	v_add_f32_e32 v240, v240, v241
	v_add_f32_e32 v242, v242, v243
	v_add_f32_e32 v244, v244, v245
	v_add_f32_e32 v230, v230, v232
	v_add_f32_e32 v234, v234, v236
	v_add_f32_e32 v238, v238, v240
	v_add_f32_e32 v242, v242, v244
	ds_bpermute_b32 v231, v171, v230
	ds_bpermute_b32 v235, v171, v234
	ds_bpermute_b32 v239, v171, v238
	ds_bpermute_b32 v243, v171, v242
	s_waitcnt lgkmcnt(0)
	v_add_f32_e32 v230, v230, v231
	v_add_f32_e32 v234, v234, v235
	v_add_f32_e32 v238, v238, v239
	v_add_f32_e32 v242, v242, v243
	ds_bpermute_b32 v231, v172, v230
	ds_bpermute_b32 v235, v172, v234
	ds_bpermute_b32 v239, v172, v238
	ds_bpermute_b32 v243, v172, v242
	s_waitcnt lgkmcnt(0)
	v_add_f32_e32 v230, v230, v231
	v_add_f32_e32 v234, v234, v235
	v_add_f32_e32 v238, v238, v239
	v_add_f32_e32 v242, v242, v243
	v_fmamk_f32 v230, v230, 0x3a800000, v152
	v_fmamk_f32 v234, v234, 0x3a800000, v152
	v_fmamk_f32 v238, v238, 0x3a800000, v152
	v_fmamk_f32 v242, v242, 0x3a800000, v152
	v_rsq_f32_e32 v230, v230
	v_rsq_f32_e32 v234, v234
	v_rsq_f32_e32 v238, v238
	v_rsq_f32_e32 v242, v242
	s_nop 0
	v_pk_mul_f32 v[116:117], v[116:117], v[230:231] op_sel_hi:[1,0]
	v_pk_mul_f32 v[118:119], v[118:119], v[230:231] op_sel_hi:[1,0]
	v_pk_mul_f32 v[112:113], v[112:113], v[230:231] op_sel_hi:[1,0]
	v_pk_mul_f32 v[114:115], v[114:115], v[230:231] op_sel_hi:[1,0]
	v_pk_mul_f32 v[124:125], v[124:125], v[230:231] op_sel_hi:[1,0]
	v_pk_mul_f32 v[126:127], v[126:127], v[230:231] op_sel_hi:[1,0]
	v_pk_mul_f32 v[120:121], v[120:121], v[230:231] op_sel_hi:[1,0]
	v_pk_mul_f32 v[122:123], v[122:123], v[230:231] op_sel_hi:[1,0]
	v_mul_f32_e32 v176, 0xbfb8aa3b, v116
	v_mul_f32_e32 v177, 0xbfb8aa3b, v117
	v_mul_f32_e32 v178, 0xbfb8aa3b, v118
	v_mul_f32_e32 v179, 0xbfb8aa3b, v119
	v_mul_f32_e32 v180, 0xbfb8aa3b, v112
	v_mul_f32_e32 v181, 0xbfb8aa3b, v113
	v_mul_f32_e32 v182, 0xbfb8aa3b, v114
	v_mul_f32_e32 v183, 0xbfb8aa3b, v115
	v_exp_f32_e32 v176, v176
	v_exp_f32_e32 v177, v177
	v_exp_f32_e32 v178, v178
	v_exp_f32_e32 v179, v179
	v_exp_f32_e32 v180, v180
	v_exp_f32_e32 v181, v181
	v_exp_f32_e32 v182, v182
	v_exp_f32_e32 v183, v183
	v_add_f32_e32 v176, 1.0, v176
	v_add_f32_e32 v177, 1.0, v177
	v_add_f32_e32 v178, 1.0, v178
	v_add_f32_e32 v179, 1.0, v179
	v_add_f32_e32 v180, 1.0, v180
	v_add_f32_e32 v181, 1.0, v181
	v_add_f32_e32 v182, 1.0, v182
	v_add_f32_e32 v183, 1.0, v183
	v_rcp_f32_e32 v176, v176
	v_rcp_f32_e32 v177, v177
	v_rcp_f32_e32 v178, v178
	v_rcp_f32_e32 v179, v179
	v_rcp_f32_e32 v180, v180
	v_rcp_f32_e32 v181, v181
	v_rcp_f32_e32 v182, v182
	v_rcp_f32_e32 v183, v183
	v_mul_f32_e32 v176, v116, v176
	v_mul_f32_e32 v177, v117, v177
	v_mul_f32_e32 v178, v118, v178
	v_mul_f32_e32 v179, v119, v179
	v_mul_f32_e32 v180, v112, v180
	v_mul_f32_e32 v181, v113, v181
	v_mul_f32_e32 v182, v114, v182
	v_mul_f32_e32 v183, v115, v183
	v_mul_f32_e32 v176, v124, v176
	v_mul_f32_e32 v177, v125, v177
	v_mul_f32_e32 v178, v126, v178
	v_mul_f32_e32 v179, v127, v179
	v_mul_f32_e32 v180, v120, v180
	v_mul_f32_e32 v181, v121, v181
	v_mul_f32_e32 v182, v122, v182
	v_mul_f32_e32 v183, v123, v183
	v_cvt_pk_bf16_f32 v192, v176, v177
	v_cvt_pk_bf16_f32 v193, v178, v179
	v_cvt_pk_bf16_f32 v194, v180, v181
	v_cvt_pk_bf16_f32 v195, v182, v183
	v_mov_b32_e32 v200, v248
	global_store_dwordx4 v200, v[192:195], s[48:49]
	v_pk_mul_f32 v[100:101], v[100:101], v[234:235] op_sel_hi:[1,0]
	v_pk_mul_f32 v[102:103], v[102:103], v[234:235] op_sel_hi:[1,0]
	v_pk_mul_f32 v[96:97], v[96:97], v[234:235] op_sel_hi:[1,0]
	v_pk_mul_f32 v[98:99], v[98:99], v[234:235] op_sel_hi:[1,0]
	v_pk_mul_f32 v[108:109], v[108:109], v[234:235] op_sel_hi:[1,0]
	v_pk_mul_f32 v[110:111], v[110:111], v[234:235] op_sel_hi:[1,0]
	v_pk_mul_f32 v[104:105], v[104:105], v[234:235] op_sel_hi:[1,0]
	v_pk_mul_f32 v[106:107], v[106:107], v[234:235] op_sel_hi:[1,0]
	v_mul_f32_e32 v184, 0xbfb8aa3b, v100
	v_mul_f32_e32 v185, 0xbfb8aa3b, v101
	v_mul_f32_e32 v186, 0xbfb8aa3b, v102
	v_mul_f32_e32 v187, 0xbfb8aa3b, v103
	v_mul_f32_e32 v188, 0xbfb8aa3b, v96
	v_mul_f32_e32 v189, 0xbfb8aa3b, v97
	v_mul_f32_e32 v190, 0xbfb8aa3b, v98
	v_mul_f32_e32 v191, 0xbfb8aa3b, v99
	v_exp_f32_e32 v184, v184
	v_exp_f32_e32 v185, v185
	v_exp_f32_e32 v186, v186
	v_exp_f32_e32 v187, v187
	v_exp_f32_e32 v188, v188
	v_exp_f32_e32 v189, v189
	v_exp_f32_e32 v190, v190
	v_exp_f32_e32 v191, v191
	v_add_f32_e32 v184, 1.0, v184
	v_add_f32_e32 v185, 1.0, v185
	v_add_f32_e32 v186, 1.0, v186
	v_add_f32_e32 v187, 1.0, v187
	v_add_f32_e32 v188, 1.0, v188
	v_add_f32_e32 v189, 1.0, v189
	v_add_f32_e32 v190, 1.0, v190
	v_add_f32_e32 v191, 1.0, v191
	v_rcp_f32_e32 v184, v184
	v_rcp_f32_e32 v185, v185
	v_rcp_f32_e32 v186, v186
	v_rcp_f32_e32 v187, v187
	v_rcp_f32_e32 v188, v188
	v_rcp_f32_e32 v189, v189
	v_rcp_f32_e32 v190, v190
	v_rcp_f32_e32 v191, v191
	v_mul_f32_e32 v184, v100, v184
	v_mul_f32_e32 v185, v101, v185
	v_mul_f32_e32 v186, v102, v186
;     __device__ __forceinline__ void operator()(const f32x4 (&acc)[2], int srow, int cgp, int kq) const { one(acc[0], srow, 2 * cgp, kq); one(acc[1], srow, 2 * cgp + 1, kq); }
;     __device__ __forceinline__ void operator()(AccRef acc, const pg8::Unit& u, int wr, int wc, int fr, int fq) const {
;         const int row0 = u.pm * 256 + wr * 64 + fr, col0 = u.pn * 128 + wc * 32 + 8 * fq;
; #pragma unroll
;         for (int ai = 0; ai < 2; ++ai)
; #pragma unroll
;             for (int m = 0; m < 4; ++m) {
;                 const int row = row0 + ai * 128 + m * 16;
;                 const float rs = rs_from(ssp + (size_t)row * 16, 4, 1.0f / 1024.0f);
;                 f32x4 o[2];
; #pragma unroll
;                 for (int n = 0; n < 2; ++n)
; #pragma unroll
;                     for (int j = 0; j < 4; ++j) {
;                         const float g = acc[ai][0][m][n][j] * rs, up = acc[ai][1][m][n][j] * rs;
;                         o[n][j] = g * __builtin_amdgcn_rcpf(1.0f + __expf(-g)) * up;
;                     }
;                 *(u32x4*)(act + (size_t)row * FF + col0) = pack8(o[0], o[1]);
;             }
	v_mul_f32_e32 v187, v103, v187
	v_mul_f32_e32 v188, v96, v188
	v_mul_f32_e32 v189, v97, v189
	v_mul_f32_e32 v190, v98, v190
	v_mul_f32_e32 v191, v99, v191
	v_mul_f32_e32 v184, v108, v184
	v_mul_f32_e32 v185, v109, v185
	v_mul_f32_e32 v186, v110, v186
	v_mul_f32_e32 v187, v111, v187
	v_mul_f32_e32 v188, v104, v188
	v_mul_f32_e32 v189, v105, v189
	v_mul_f32_e32 v190, v106, v190
	v_mul_f32_e32 v191, v107, v191
	v_cvt_pk_bf16_f32 v196, v184, v185
	v_cvt_pk_bf16_f32 v197, v186, v187
	v_cvt_pk_bf16_f32 v198, v188, v189
	v_cvt_pk_bf16_f32 v199, v190, v191
	v_add_u32_e32 v201, 0x16000, v248
	global_store_dwordx4 v201, v[196:199], s[48:49]
	v_pk_mul_f32 v[84:85], v[84:85], v[238:239] op_sel_hi:[1,0]
	v_pk_mul_f32 v[86:87], v[86:87], v[238:239] op_sel_hi:[1,0]
	v_pk_mul_f32 v[80:81], v[80:81], v[238:239] op_sel_hi:[1,0]
	v_pk_mul_f32 v[82:83], v[82:83], v[238:239] op_sel_hi:[1,0]
	v_pk_mul_f32 v[92:93], v[92:93], v[238:239] op_sel_hi:[1,0]
	v_pk_mul_f32 v[94:95], v[94:95], v[238:239] op_sel_hi:[1,0]
	v_pk_mul_f32 v[88:89], v[88:89], v[238:239] op_sel_hi:[1,0]
	v_pk_mul_f32 v[90:91], v[90:91], v[238:239] op_sel_hi:[1,0]
	v_mul_f32_e32 v176, 0xbfb8aa3b, v84
	v_mul_f32_e32 v177, 0xbfb8aa3b, v85
	v_mul_f32_e32 v178, 0xbfb8aa3b, v86
	v_mul_f32_e32 v179, 0xbfb8aa3b, v87
	v_mul_f32_e32 v180, 0xbfb8aa3b, v80
	v_mul_f32_e32 v181, 0xbfb8aa3b, v81
	v_mul_f32_e32 v182, 0xbfb8aa3b, v82
	v_mul_f32_e32 v183, 0xbfb8aa3b, v83
	v_exp_f32_e32 v176, v176
	v_exp_f32_e32 v177, v177
	v_exp_f32_e32 v178, v178
	v_exp_f32_e32 v179, v179
	v_exp_f32_e32 v180, v180
	v_exp_f32_e32 v181, v181
	v_exp_f32_e32 v182, v182
	v_exp_f32_e32 v183, v183
	v_add_f32_e32 v176, 1.0, v176
	v_add_f32_e32 v177, 1.0, v177
	v_add_f32_e32 v178, 1.0, v178
	v_add_f32_e32 v179, 1.0, v179
	v_add_f32_e32 v180, 1.0, v180
	v_add_f32_e32 v181, 1.0, v181
	v_add_f32_e32 v182, 1.0, v182
	v_add_f32_e32 v183, 1.0, v183
	v_rcp_f32_e32 v176, v176
	v_rcp_f32_e32 v177, v177
	v_rcp_f32_e32 v178, v178
	v_rcp_f32_e32 v179, v179
	v_rcp_f32_e32 v180, v180
	v_rcp_f32_e32 v181, v181
	v_rcp_f32_e32 v182, v182
	v_rcp_f32_e32 v183, v183
	v_mul_f32_e32 v176, v84, v176
	v_mul_f32_e32 v177, v85, v177
	v_mul_f32_e32 v178, v86, v178
	v_mul_f32_e32 v179, v87, v179
	v_mul_f32_e32 v180, v80, v180
	v_mul_f32_e32 v181, v81, v181
	v_mul_f32_e32 v182, v82, v182
	v_mul_f32_e32 v183, v83, v183
	v_mul_f32_e32 v176, v92, v176
	v_mul_f32_e32 v177, v93, v177
	v_mul_f32_e32 v178, v94, v178
	v_mul_f32_e32 v179, v95, v179
	v_mul_f32_e32 v180, v88, v180
	v_mul_f32_e32 v181, v89, v181
	v_mul_f32_e32 v182, v90, v182
	v_mul_f32_e32 v183, v91, v183
	v_cvt_pk_bf16_f32 v192, v176, v177
	v_cvt_pk_bf16_f32 v193, v178, v179
	v_cvt_pk_bf16_f32 v194, v180, v181
	v_cvt_pk_bf16_f32 v195, v182, v183
	v_add_u32_e32 v200, 0x2c000, v248
	global_store_dwordx4 v200, v[192:195], s[48:49]
	v_pk_mul_f32 v[68:69], v[68:69], v[242:243] op_sel_hi:[1,0]
	v_pk_mul_f32 v[70:71], v[70:71], v[242:243] op_sel_hi:[1,0]
	v_pk_mul_f32 v[64:65], v[64:65], v[242:243] op_sel_hi:[1,0]
	v_pk_mul_f32 v[66:67], v[66:67], v[242:243] op_sel_hi:[1,0]
	v_pk_mul_f32 v[76:77], v[76:77], v[242:243] op_sel_hi:[1,0]
	v_pk_mul_f32 v[78:79], v[78:79], v[242:243] op_sel_hi:[1,0]
	v_pk_mul_f32 v[72:73], v[72:73], v[242:243] op_sel_hi:[1,0]
	v_pk_mul_f32 v[74:75], v[74:75], v[242:243] op_sel_hi:[1,0]
	v_mul_f32_e32 v184, 0xbfb8aa3b, v68
	v_mul_f32_e32 v185, 0xbfb8aa3b, v69
	v_mul_f32_e32 v186, 0xbfb8aa3b, v70
	v_mul_f32_e32 v187, 0xbfb8aa3b, v71
	v_mul_f32_e32 v188, 0xbfb8aa3b, v64
	v_mul_f32_e32 v189, 0xbfb8aa3b, v65
	v_mul_f32_e32 v190, 0xbfb8aa3b, v66
	v_mul_f32_e32 v191, 0xbfb8aa3b, v67
	v_exp_f32_e32 v184, v184
	v_exp_f32_e32 v185, v185
	v_exp_f32_e32 v186, v186
	v_exp_f32_e32 v187, v187
	v_exp_f32_e32 v188, v188
	v_exp_f32_e32 v189, v189
	v_exp_f32_e32 v190, v190
	v_exp_f32_e32 v191, v191
	v_add_f32_e32 v184, 1.0, v184
	v_add_f32_e32 v185, 1.0, v185
	v_add_f32_e32 v186, 1.0, v186
	v_add_f32_e32 v187, 1.0, v187
	v_add_f32_e32 v188, 1.0, v188
	v_add_f32_e32 v189, 1.0, v189
	v_add_f32_e32 v190, 1.0, v190
	v_add_f32_e32 v191, 1.0, v191
	v_rcp_f32_e32 v184, v184
	v_rcp_f32_e32 v185, v185
	v_rcp_f32_e32 v186, v186
	v_rcp_f32_e32 v187, v187
	v_rcp_f32_e32 v188, v188
	v_rcp_f32_e32 v189, v189
	v_rcp_f32_e32 v190, v190
	v_rcp_f32_e32 v191, v191
	v_mul_f32_e32 v184, v68, v184
	v_mul_f32_e32 v185, v69, v185
	v_mul_f32_e32 v186, v70, v186
	v_mul_f32_e32 v187, v71, v187
	v_mul_f32_e32 v188, v64, v188
	v_mul_f32_e32 v189, v65, v189
	v_mul_f32_e32 v190, v66, v190
	v_mul_f32_e32 v191, v67, v191
	v_mul_f32_e32 v184, v76, v184
	v_mul_f32_e32 v185, v77, v185
	v_mul_f32_e32 v186, v78, v186
	v_mul_f32_e32 v187, v79, v187
	v_mul_f32_e32 v188, v72, v188
	v_mul_f32_e32 v189, v73, v189
	v_mul_f32_e32 v190, v74, v190
	v_mul_f32_e32 v191, v75, v191
	v_cvt_pk_bf16_f32 v196, v184, v185
	v_cvt_pk_bf16_f32 v197, v186, v187
	v_cvt_pk_bf16_f32 v198, v188, v189
	v_cvt_pk_bf16_f32 v199, v190, v191
	v_add_u32_e32 v201, 0x42000, v248
	global_store_dwordx4 v201, v[196:199], s[48:49]
	s_waitcnt vmcnt(4)
	v_add_f32_e32 v154, v154, v155
	v_add_f32_e32 v156, v156, v157
	v_add_f32_e32 v158, v158, v159
	v_add_f32_e32 v160, v160, v161
	v_add_f32_e32 v162, v162, v163
	v_add_f32_e32 v164, v164, v165
	v_add_f32_e32 v166, v166, v167
	v_add_f32_e32 v168, v168, v169
	v_add_f32_e32 v154, v154, v156
	v_add_f32_e32 v158, v158, v160
	v_add_f32_e32 v162, v162, v164
	v_add_f32_e32 v166, v166, v168
	ds_bpermute_b32 v155, v171, v154
	ds_bpermute_b32 v159, v171, v158
	ds_bpermute_b32 v163, v171, v162
	ds_bpermute_b32 v167, v171, v166
	s_waitcnt lgkmcnt(0)
;     __device__ __forceinline__ void operator()(const f32x4 (&acc)[2], int srow, int cgp, int kq) const { one(acc[0], srow, 2 * cgp, kq); one(acc[1], srow, 2 * cgp + 1, kq); }
;     __device__ __forceinline__ void operator()(AccRef acc, const pg8::Unit& u, int wr, int wc, int fr, int fq) const {
;         const int row0 = u.pm * 256 + wr * 64 + fr, col0 = u.pn * 128 + wc * 32 + 8 * fq;
; #pragma unroll
;         for (int ai = 0; ai < 2; ++ai)
; #pragma unroll
;             for (int m = 0; m < 4; ++m) {
;                 const int row = row0 + ai * 128 + m * 16;
;                 const float rs = rs_from(ssp + (size_t)row * 16, 4, 1.0f / 1024.0f);
;                 f32x4 o[2];
; #pragma unroll
;                 for (int n = 0; n < 2; ++n)
; #pragma unroll
;                     for (int j = 0; j < 4; ++j) {
;                         const float g = acc[ai][0][m][n][j] * rs, up = acc[ai][1][m][n][j] * rs;
;                         o[n][j] = g * __builtin_amdgcn_rcpf(1.0f + __expf(-g)) * up;
;                     }
;                 *(u32x4*)(act + (size_t)row * FF + col0) = pack8(o[0], o[1]);
;             }
	v_add_f32_e32 v154, v154, v155
	v_add_f32_e32 v158, v158, v159
	v_add_f32_e32 v162, v162, v163
	v_add_f32_e32 v166, v166, v167
	ds_bpermute_b32 v155, v172, v154
	ds_bpermute_b32 v159, v172, v158
	ds_bpermute_b32 v163, v172, v162
	ds_bpermute_b32 v167, v172, v166
	s_waitcnt lgkmcnt(0)
	v_add_f32_e32 v154, v154, v155
	v_add_f32_e32 v158, v158, v159
	v_add_f32_e32 v162, v162, v163
	v_add_f32_e32 v166, v166, v167
	v_fmamk_f32 v154, v154, 0x3a800000, v152
	v_fmamk_f32 v158, v158, 0x3a800000, v152
	v_fmamk_f32 v162, v162, 0x3a800000, v152
	v_fmamk_f32 v166, v166, 0x3a800000, v152
	v_rsq_f32_e32 v154, v154
	v_rsq_f32_e32 v158, v158
	v_rsq_f32_e32 v162, v162
	v_rsq_f32_e32 v166, v166
	s_nop 0
	v_pk_mul_f32 v[52:53], v[52:53], v[154:155] op_sel_hi:[1,0]
	v_pk_mul_f32 v[54:55], v[54:55], v[154:155] op_sel_hi:[1,0]
	v_pk_mul_f32 v[48:49], v[48:49], v[154:155] op_sel_hi:[1,0]
	v_pk_mul_f32 v[50:51], v[50:51], v[154:155] op_sel_hi:[1,0]
	v_pk_mul_f32 v[60:61], v[60:61], v[154:155] op_sel_hi:[1,0]
	v_pk_mul_f32 v[62:63], v[62:63], v[154:155] op_sel_hi:[1,0]
	v_pk_mul_f32 v[56:57], v[56:57], v[154:155] op_sel_hi:[1,0]
	v_pk_mul_f32 v[58:59], v[58:59], v[154:155] op_sel_hi:[1,0]
	v_mul_f32_e32 v176, 0xbfb8aa3b, v52
	v_mul_f32_e32 v177, 0xbfb8aa3b, v53
	v_mul_f32_e32 v178, 0xbfb8aa3b, v54
	v_mul_f32_e32 v179, 0xbfb8aa3b, v55
	v_mul_f32_e32 v180, 0xbfb8aa3b, v48
	v_mul_f32_e32 v181, 0xbfb8aa3b, v49
	v_mul_f32_e32 v182, 0xbfb8aa3b, v50
	v_mul_f32_e32 v183, 0xbfb8aa3b, v51
	v_exp_f32_e32 v176, v176
	v_exp_f32_e32 v177, v177
	v_exp_f32_e32 v178, v178
	v_exp_f32_e32 v179, v179
	v_exp_f32_e32 v180, v180
	v_exp_f32_e32 v181, v181
	v_exp_f32_e32 v182, v182
	v_exp_f32_e32 v183, v183
	v_add_f32_e32 v176, 1.0, v176
	v_add_f32_e32 v177, 1.0, v177
	v_add_f32_e32 v178, 1.0, v178
	v_add_f32_e32 v179, 1.0, v179
	v_add_f32_e32 v180, 1.0, v180
	v_add_f32_e32 v181, 1.0, v181
	v_add_f32_e32 v182, 1.0, v182
	v_add_f32_e32 v183, 1.0, v183
	v_rcp_f32_e32 v176, v176
	v_rcp_f32_e32 v177, v177
	v_rcp_f32_e32 v178, v178
	v_rcp_f32_e32 v179, v179
	v_rcp_f32_e32 v180, v180
	v_rcp_f32_e32 v181, v181
	v_rcp_f32_e32 v182, v182
	v_rcp_f32_e32 v183, v183
	v_mul_f32_e32 v176, v52, v176
	v_mul_f32_e32 v177, v53, v177
	v_mul_f32_e32 v178, v54, v178
	v_mul_f32_e32 v179, v55, v179
	v_mul_f32_e32 v180, v48, v180
	v_mul_f32_e32 v181, v49, v181
	v_mul_f32_e32 v182, v50, v182
	v_mul_f32_e32 v183, v51, v183
	v_mul_f32_e32 v176, v60, v176
	v_mul_f32_e32 v177, v61, v177
	v_mul_f32_e32 v178, v62, v178
	v_mul_f32_e32 v179, v63, v179
	v_mul_f32_e32 v180, v56, v180
	v_mul_f32_e32 v181, v57, v181
	v_mul_f32_e32 v182, v58, v182
	v_mul_f32_e32 v183, v59, v183
	v_cvt_pk_bf16_f32 v192, v176, v177
	v_cvt_pk_bf16_f32 v193, v178, v179
	v_cvt_pk_bf16_f32 v194, v180, v181
	v_cvt_pk_bf16_f32 v195, v182, v183
	v_add_u32_e32 v200, 0xb0000, v248
	global_store_dwordx4 v200, v[192:195], s[48:49]
	v_pk_mul_f32 v[36:37], v[36:37], v[158:159] op_sel_hi:[1,0]
	v_pk_mul_f32 v[38:39], v[38:39], v[158:159] op_sel_hi:[1,0]
	v_pk_mul_f32 v[32:33], v[32:33], v[158:159] op_sel_hi:[1,0]
	v_pk_mul_f32 v[34:35], v[34:35], v[158:159] op_sel_hi:[1,0]
	v_pk_mul_f32 v[44:45], v[44:45], v[158:159] op_sel_hi:[1,0]
	v_pk_mul_f32 v[46:47], v[46:47], v[158:159] op_sel_hi:[1,0]
	v_pk_mul_f32 v[40:41], v[40:41], v[158:159] op_sel_hi:[1,0]
	v_pk_mul_f32 v[42:43], v[42:43], v[158:159] op_sel_hi:[1,0]
	v_mul_f32_e32 v184, 0xbfb8aa3b, v36
	v_mul_f32_e32 v185, 0xbfb8aa3b, v37
	v_mul_f32_e32 v186, 0xbfb8aa3b, v38
	v_mul_f32_e32 v187, 0xbfb8aa3b, v39
	v_mul_f32_e32 v188, 0xbfb8aa3b, v32
	v_mul_f32_e32 v189, 0xbfb8aa3b, v33
	v_mul_f32_e32 v190, 0xbfb8aa3b, v34
	v_mul_f32_e32 v191, 0xbfb8aa3b, v35
	v_exp_f32_e32 v184, v184
	v_exp_f32_e32 v185, v185
	v_exp_f32_e32 v186, v186
	v_exp_f32_e32 v187, v187
	v_exp_f32_e32 v188, v188
	v_exp_f32_e32 v189, v189
	v_exp_f32_e32 v190, v190
	v_exp_f32_e32 v191, v191
	v_add_f32_e32 v184, 1.0, v184
	v_add_f32_e32 v185, 1.0, v185
	v_add_f32_e32 v186, 1.0, v186
	v_add_f32_e32 v187, 1.0, v187
	v_add_f32_e32 v188, 1.0, v188
	v_add_f32_e32 v189, 1.0, v189
	v_add_f32_e32 v190, 1.0, v190
	v_add_f32_e32 v191, 1.0, v191
	v_rcp_f32_e32 v184, v184
	v_rcp_f32_e32 v185, v185
	v_rcp_f32_e32 v186, v186
	v_rcp_f32_e32 v187, v187
	v_rcp_f32_e32 v188, v188
	v_rcp_f32_e32 v189, v189
	v_rcp_f32_e32 v190, v190
	v_rcp_f32_e32 v191, v191
	v_mul_f32_e32 v184, v36, v184
	v_mul_f32_e32 v185, v37, v185
	v_mul_f32_e32 v186, v38, v186
	v_mul_f32_e32 v187, v39, v187
	v_mul_f32_e32 v188, v32, v188
	v_mul_f32_e32 v189, v33, v189
	v_mul_f32_e32 v190, v34, v190
	v_mul_f32_e32 v191, v35, v191
	v_mul_f32_e32 v184, v44, v184
	v_mul_f32_e32 v185, v45, v185
	v_mul_f32_e32 v186, v46, v186
	v_mul_f32_e32 v187, v47, v187
	v_mul_f32_e32 v188, v40, v188
	v_mul_f32_e32 v189, v41, v189
;     __device__ __forceinline__ void operator()(const f32x4 (&acc)[2], int srow, int cgp, int kq) const { one(acc[0], srow, 2 * cgp, kq); one(acc[1], srow, 2 * cgp + 1, kq); }
;     __device__ __forceinline__ void operator()(AccRef acc, const pg8::Unit& u, int wr, int wc, int fr, int fq) const {
;         const int row0 = u.pm * 256 + wr * 64 + fr, col0 = u.pn * 128 + wc * 32 + 8 * fq;
; #pragma unroll
;         for (int ai = 0; ai < 2; ++ai)
; #pragma unroll
;             for (int m = 0; m < 4; ++m) {
;                 const int row = row0 + ai * 128 + m * 16;
;                 const float rs = rs_from(ssp + (size_t)row * 16, 4, 1.0f / 1024.0f);
;                 f32x4 o[2];
; #pragma unroll
;                 for (int n = 0; n < 2; ++n)
; #pragma unroll
;                     for (int j = 0; j < 4; ++j) {
;                         const float g = acc[ai][0][m][n][j] * rs, up = acc[ai][1][m][n][j] * rs;
;                         o[n][j] = g * __builtin_amdgcn_rcpf(1.0f + __expf(-g)) * up;
;                     }
;                 *(u32x4*)(act + (size_t)row * FF + col0) = pack8(o[0], o[1]);
;             }
	v_mul_f32_e32 v190, v42, v190
	v_mul_f32_e32 v191, v43, v191
	v_cvt_pk_bf16_f32 v196, v184, v185
	v_cvt_pk_bf16_f32 v197, v186, v187
	v_cvt_pk_bf16_f32 v198, v188, v189
	v_cvt_pk_bf16_f32 v199, v190, v191
	v_add_u32_e32 v201, 0xc6000, v248
	global_store_dwordx4 v201, v[196:199], s[48:49]
	v_pk_mul_f32 v[20:21], v[20:21], v[162:163] op_sel_hi:[1,0]
	v_pk_mul_f32 v[22:23], v[22:23], v[162:163] op_sel_hi:[1,0]
	v_pk_mul_f32 v[16:17], v[16:17], v[162:163] op_sel_hi:[1,0]
	v_pk_mul_f32 v[18:19], v[18:19], v[162:163] op_sel_hi:[1,0]
	v_pk_mul_f32 v[28:29], v[28:29], v[162:163] op_sel_hi:[1,0]
	v_pk_mul_f32 v[30:31], v[30:31], v[162:163] op_sel_hi:[1,0]
	v_pk_mul_f32 v[24:25], v[24:25], v[162:163] op_sel_hi:[1,0]
	v_pk_mul_f32 v[26:27], v[26:27], v[162:163] op_sel_hi:[1,0]
	v_mul_f32_e32 v176, 0xbfb8aa3b, v20
	v_mul_f32_e32 v177, 0xbfb8aa3b, v21
	v_mul_f32_e32 v178, 0xbfb8aa3b, v22
	v_mul_f32_e32 v179, 0xbfb8aa3b, v23
	v_mul_f32_e32 v180, 0xbfb8aa3b, v16
	v_mul_f32_e32 v181, 0xbfb8aa3b, v17
	v_mul_f32_e32 v182, 0xbfb8aa3b, v18
	v_mul_f32_e32 v183, 0xbfb8aa3b, v19
	v_exp_f32_e32 v176, v176
	v_exp_f32_e32 v177, v177
	v_exp_f32_e32 v178, v178
	v_exp_f32_e32 v179, v179
	v_exp_f32_e32 v180, v180
	v_exp_f32_e32 v181, v181
	v_exp_f32_e32 v182, v182
	v_exp_f32_e32 v183, v183
	v_add_f32_e32 v176, 1.0, v176
	v_add_f32_e32 v177, 1.0, v177
	v_add_f32_e32 v178, 1.0, v178
	v_add_f32_e32 v179, 1.0, v179
	v_add_f32_e32 v180, 1.0, v180
	v_add_f32_e32 v181, 1.0, v181
	v_add_f32_e32 v182, 1.0, v182
	v_add_f32_e32 v183, 1.0, v183
	v_rcp_f32_e32 v176, v176
	v_rcp_f32_e32 v177, v177
	v_rcp_f32_e32 v178, v178
	v_rcp_f32_e32 v179, v179
	v_rcp_f32_e32 v180, v180
	v_rcp_f32_e32 v181, v181
	v_rcp_f32_e32 v182, v182
	v_rcp_f32_e32 v183, v183
	v_mul_f32_e32 v176, v20, v176
	v_mul_f32_e32 v177, v21, v177
	v_mul_f32_e32 v178, v22, v178
	v_mul_f32_e32 v179, v23, v179
	v_mul_f32_e32 v180, v16, v180
	v_mul_f32_e32 v181, v17, v181
	v_mul_f32_e32 v182, v18, v182
	v_mul_f32_e32 v183, v19, v183
	v_mul_f32_e32 v176, v28, v176
	v_mul_f32_e32 v177, v29, v177
	v_mul_f32_e32 v178, v30, v178
	v_mul_f32_e32 v179, v31, v179
	v_mul_f32_e32 v180, v24, v180
	v_mul_f32_e32 v181, v25, v181
	v_mul_f32_e32 v182, v26, v182
	v_mul_f32_e32 v183, v27, v183
	v_cvt_pk_bf16_f32 v192, v176, v177
	v_cvt_pk_bf16_f32 v193, v178, v179
	v_cvt_pk_bf16_f32 v194, v180, v181
	v_cvt_pk_bf16_f32 v195, v182, v183
	v_add_u32_e32 v200, 0xdc000, v248
	global_store_dwordx4 v200, v[192:195], s[48:49]
	v_pk_mul_f32 v[4:5], v[4:5], v[166:167] op_sel_hi:[1,0]
	v_pk_mul_f32 v[6:7], v[6:7], v[166:167] op_sel_hi:[1,0]
	v_pk_mul_f32 v[0:1], v[0:1], v[166:167] op_sel_hi:[1,0]
	v_pk_mul_f32 v[2:3], v[2:3], v[166:167] op_sel_hi:[1,0]
	v_pk_mul_f32 v[12:13], v[12:13], v[166:167] op_sel_hi:[1,0]
	v_pk_mul_f32 v[14:15], v[14:15], v[166:167] op_sel_hi:[1,0]
	v_pk_mul_f32 v[8:9], v[8:9], v[166:167] op_sel_hi:[1,0]
	v_pk_mul_f32 v[10:11], v[10:11], v[166:167] op_sel_hi:[1,0]
	v_mul_f32_e32 v184, 0xbfb8aa3b, v4
	v_mul_f32_e32 v185, 0xbfb8aa3b, v5
	v_mul_f32_e32 v186, 0xbfb8aa3b, v6
	v_mul_f32_e32 v187, 0xbfb8aa3b, v7
	v_mul_f32_e32 v188, 0xbfb8aa3b, v0
	v_mul_f32_e32 v189, 0xbfb8aa3b, v1
	v_mul_f32_e32 v190, 0xbfb8aa3b, v2
	v_mul_f32_e32 v191, 0xbfb8aa3b, v3
	v_exp_f32_e32 v184, v184
	v_exp_f32_e32 v185, v185
	v_exp_f32_e32 v186, v186
	v_exp_f32_e32 v187, v187
	v_exp_f32_e32 v188, v188
	v_exp_f32_e32 v189, v189
	v_exp_f32_e32 v190, v190
	v_exp_f32_e32 v191, v191
	v_add_f32_e32 v184, 1.0, v184
	v_add_f32_e32 v185, 1.0, v185
	v_add_f32_e32 v186, 1.0, v186
	v_add_f32_e32 v187, 1.0, v187
	v_add_f32_e32 v188, 1.0, v188
	v_add_f32_e32 v189, 1.0, v189
	v_add_f32_e32 v190, 1.0, v190
	v_add_f32_e32 v191, 1.0, v191
	v_rcp_f32_e32 v184, v184
	v_rcp_f32_e32 v185, v185
	v_rcp_f32_e32 v186, v186
	v_rcp_f32_e32 v187, v187
	v_rcp_f32_e32 v188, v188
	v_rcp_f32_e32 v189, v189
	v_rcp_f32_e32 v190, v190
	v_rcp_f32_e32 v191, v191
	v_mul_f32_e32 v184, v4, v184
	v_mul_f32_e32 v185, v5, v185
	v_mul_f32_e32 v186, v6, v186
	v_mul_f32_e32 v187, v7, v187
	v_mul_f32_e32 v188, v0, v188
	v_mul_f32_e32 v189, v1, v189
	v_mul_f32_e32 v190, v2, v190
	v_mul_f32_e32 v191, v3, v191
	v_mul_f32_e32 v184, v12, v184
	v_mul_f32_e32 v185, v13, v185
	v_mul_f32_e32 v186, v14, v186
	v_mul_f32_e32 v187, v15, v187
	v_mul_f32_e32 v188, v8, v188
	v_mul_f32_e32 v189, v9, v189
	v_mul_f32_e32 v190, v10, v190
	v_mul_f32_e32 v191, v11, v191
	v_cvt_pk_bf16_f32 v196, v184, v185
	v_cvt_pk_bf16_f32 v197, v186, v187
	v_cvt_pk_bf16_f32 v198, v188, v189
	v_cvt_pk_bf16_f32 v199, v190, v191
	v_add_u32_e32 v201, 0xf2000, v248
	global_store_dwordx4 v201, v[196:199], s[48:49]
.Lswi_end0:
	s_and_b64 vcc, exec, s[2:3]
	s_mov_b64 s[2:3], -1
	s_cbranch_vccnz .LBB0_364
	s_andn2_b64 vcc, exec, s[10:11]
	s_cbranch_vccnz .LBB0_363
	s_barrier
	s_branch .LBB0_363

;     __device__ __forceinline__ void operator()(const f32x4 (&acc)[2], int srow, int cgp, int kq) const { one(acc[0], srow, 2 * cgp, kq); one(acc[1], srow, 2 * cgp + 1, kq); }
;     __device__ __forceinline__ void operator()(AccRef acc, const pg8::Unit& u, int wr, int wc, int fr, int fq) const {
;         const int row0 = u.pm * 256 + wr * 64 + fr, col0 = u.pn * 128 + wc * 32 + 8 * fq;
; #pragma unroll
;         for (int ai = 0; ai < 2; ++ai)
; #pragma unroll
;             for (int m = 0; m < 4; ++m) {
;                 const int row = row0 + ai * 128 + m * 16;
;                 const float rs = rs_from(ssp + (size_t)row * 16, 4, 1.0f / 1024.0f);
;                 f32x4 o[2];
; #pragma unroll
;                 for (int n = 0; n < 2; ++n)
; #pragma unroll
;                     for (int j = 0; j < 4; ++j) {
;                         const float g = acc[ai][0][m][n][j] * rs, up = acc[ai][1][m][n][j] * rs;
;                         o[n][j] = g * __builtin_amdgcn_rcpf(1.0f + __expf(-g)) * up;
;                     }
;                 *(u32x4*)(act + (size_t)row * FF + col0) = pack8(o[0], o[1]);
;             }
.LBB0_1320:
.Lswi_beg1:
	v_add_u32_e32 v249, 0x2000, v247
	global_load_dwordx4 v[154:157], v249, s[46:47]
	global_load_dwordx4 v[158:161], v249, s[46:47] offset:1024
	global_load_dwordx4 v[162:165], v249, s[46:47] offset:2048
	global_load_dwordx4 v[166:169], v249, s[46:47] offset:3072
	v_mbcnt_lo_u32_b32 v170, -1, 0
	v_mbcnt_hi_u32_b32 v170, -1, v170
	v_xor_b32_e32 v171, 16, v170
	v_xor_b32_e32 v172, 32, v170
	v_lshlrev_b32_e32 v171, 2, v171
	v_lshlrev_b32_e32 v172, 2, v172
	v_lshl_or_b32 v173, s61, 7, v148
	v_lshlrev_b32_e32 v173, 1, v173
	v_mad_u32_u24 v248, v246, s57, v173
	s_waitcnt vmcnt(12)
	v_add_f32_e32 v230, v230, v231
	v_add_f32_e32 v232, v232, v233
	v_add_f32_e32 v234, v234, v235
	v_add_f32_e32 v236, v236, v237
	v_add_f32_e32 v238, v238, v239
	v_add_f32_e32 v240, v240, v241
	v_add_f32_e32 v242, v242, v243
	v_add_f32_e32 v244, v244, v245
	v_add_f32_e32 v230, v230, v232
	v_add_f32_e32 v234, v234, v236
	v_add_f32_e32 v238, v238, v240
	v_add_f32_e32 v242, v242, v244
	ds_bpermute_b32 v231, v171, v230
	ds_bpermute_b32 v235, v171, v234
	ds_bpermute_b32 v239, v171, v238
	ds_bpermute_b32 v243, v171, v242
	s_waitcnt lgkmcnt(0)
	v_add_f32_e32 v230, v230, v231
	v_add_f32_e32 v234, v234, v235
	v_add_f32_e32 v238, v238, v239
	v_add_f32_e32 v242, v242, v243
	ds_bpermute_b32 v231, v172, v230
	ds_bpermute_b32 v235, v172, v234
	ds_bpermute_b32 v239, v172, v238
	ds_bpermute_b32 v243, v172, v242
	s_waitcnt lgkmcnt(0)
	v_add_f32_e32 v230, v230, v231
	v_add_f32_e32 v234, v234, v235
	v_add_f32_e32 v238, v238, v239
	v_add_f32_e32 v242, v242, v243
	v_fmamk_f32 v230, v230, 0x3a800000, v152
	v_fmamk_f32 v234, v234, 0x3a800000, v152
	v_fmamk_f32 v238, v238, 0x3a800000, v152
	v_fmamk_f32 v242, v242, 0x3a800000, v152
	v_rsq_f32_e32 v230, v230
	v_rsq_f32_e32 v234, v234
	v_rsq_f32_e32 v238, v238
	v_rsq_f32_e32 v242, v242
	s_nop 0
	v_pk_mul_f32 v[116:117], v[116:117], v[230:231] op_sel_hi:[1,0]
	v_pk_mul_f32 v[118:119], v[118:119], v[230:231] op_sel_hi:[1,0]
	v_pk_mul_f32 v[112:113], v[112:113], v[230:231] op_sel_hi:[1,0]
	v_pk_mul_f32 v[114:115], v[114:115], v[230:231] op_sel_hi:[1,0]
	v_pk_mul_f32 v[124:125], v[124:125], v[230:231] op_sel_hi:[1,0]
	v_pk_mul_f32 v[126:127], v[126:127], v[230:231] op_sel_hi:[1,0]
	v_pk_mul_f32 v[120:121], v[120:121], v[230:231] op_sel_hi:[1,0]
	v_pk_mul_f32 v[122:123], v[122:123], v[230:231] op_sel_hi:[1,0]
	v_mul_f32_e32 v176, 0xbfb8aa3b, v116
	v_mul_f32_e32 v177, 0xbfb8aa3b, v117
	v_mul_f32_e32 v178, 0xbfb8aa3b, v118
	v_mul_f32_e32 v179, 0xbfb8aa3b, v119
	v_mul_f32_e32 v180, 0xbfb8aa3b, v112
	v_mul_f32_e32 v181, 0xbfb8aa3b, v113
	v_mul_f32_e32 v182, 0xbfb8aa3b, v114
	v_mul_f32_e32 v183, 0xbfb8aa3b, v115
	v_exp_f32_e32 v176, v176
	v_exp_f32_e32 v177, v177
	v_exp_f32_e32 v178, v178
	v_exp_f32_e32 v179, v179
	v_exp_f32_e32 v180, v180
	v_exp_f32_e32 v181, v181
	v_exp_f32_e32 v182, v182
	v_exp_f32_e32 v183, v183
	v_add_f32_e32 v176, 1.0, v176
	v_add_f32_e32 v177, 1.0, v177
	v_add_f32_e32 v178, 1.0, v178
	v_add_f32_e32 v179, 1.0, v179
	v_add_f32_e32 v180, 1.0, v180
	v_add_f32_e32 v181, 1.0, v181
	v_add_f32_e32 v182, 1.0, v182
	v_add_f32_e32 v183, 1.0, v183
	v_rcp_f32_e32 v176, v176
	v_rcp_f32_e32 v177, v177
	v_rcp_f32_e32 v178, v178
	v_rcp_f32_e32 v179, v179
	v_rcp_f32_e32 v180, v180
	v_rcp_f32_e32 v181, v181
	v_rcp_f32_e32 v182, v182
	v_rcp_f32_e32 v183, v183
	v_mul_f32_e32 v176, v116, v176
	v_mul_f32_e32 v177, v117, v177
	v_mul_f32_e32 v178, v118, v178
	v_mul_f32_e32 v179, v119, v179
	v_mul_f32_e32 v180, v112, v180
	v_mul_f32_e32 v181, v113, v181
	v_mul_f32_e32 v182, v114, v182
	v_mul_f32_e32 v183, v115, v183
	v_mul_f32_e32 v176, v124, v176
	v_mul_f32_e32 v177, v125, v177
	v_mul_f32_e32 v178, v126, v178
	v_mul_f32_e32 v179, v127, v179
	v_mul_f32_e32 v180, v120, v180
	v_mul_f32_e32 v181, v121, v181
	v_mul_f32_e32 v182, v122, v182
	v_mul_f32_e32 v183, v123, v183
	v_cvt_pk_bf16_f32 v192, v176, v177
	v_cvt_pk_bf16_f32 v193, v178, v179
	v_cvt_pk_bf16_f32 v194, v180, v181
	v_cvt_pk_bf16_f32 v195, v182, v183
	v_mov_b32_e32 v200, v248
	global_store_dwordx4 v200, v[192:195], s[48:49]
	v_pk_mul_f32 v[100:101], v[100:101], v[234:235] op_sel_hi:[1,0]
	v_pk_mul_f32 v[102:103], v[102:103], v[234:235] op_sel_hi:[1,0]
	v_pk_mul_f32 v[96:97], v[96:97], v[234:235] op_sel_hi:[1,0]
	v_pk_mul_f32 v[98:99], v[98:99], v[234:235] op_sel_hi:[1,0]
	v_pk_mul_f32 v[108:109], v[108:109], v[234:235] op_sel_hi:[1,0]
	v_pk_mul_f32 v[110:111], v[110:111], v[234:235] op_sel_hi:[1,0]
	v_pk_mul_f32 v[104:105], v[104:105], v[234:235] op_sel_hi:[1,0]
	v_pk_mul_f32 v[106:107], v[106:107], v[234:235] op_sel_hi:[1,0]
	v_mul_f32_e32 v184, 0xbfb8aa3b, v100
	v_mul_f32_e32 v185, 0xbfb8aa3b, v101
	v_mul_f32_e32 v186, 0xbfb8aa3b, v102
	v_mul_f32_e32 v187, 0xbfb8aa3b, v103
	v_mul_f32_e32 v188, 0xbfb8aa3b, v96
	v_mul_f32_e32 v189, 0xbfb8aa3b, v97
	v_mul_f32_e32 v190, 0xbfb8aa3b, v98
	v_mul_f32_e32 v191, 0xbfb8aa3b, v99
	v_exp_f32_e32 v184, v184
	v_exp_f32_e32 v185, v185
	v_exp_f32_e32 v186, v186
	v_exp_f32_e32 v187, v187
	v_exp_f32_e32 v188, v188
	v_exp_f32_e32 v189, v189
	v_exp_f32_e32 v190, v190
	v_exp_f32_e32 v191, v191
	v_add_f32_e32 v184, 1.0, v184
	v_add_f32_e32 v185, 1.0, v185
	v_add_f32_e32 v186, 1.0, v186
	v_add_f32_e32 v187, 1.0, v187
	v_add_f32_e32 v188, 1.0, v188
	v_add_f32_e32 v189, 1.0, v189
	v_add_f32_e32 v190, 1.0, v190
	v_add_f32_e32 v191, 1.0, v191
	v_rcp_f32_e32 v184, v184
	v_rcp_f32_e32 v185, v185
	v_rcp_f32_e32 v186, v186
	v_rcp_f32_e32 v187, v187
	v_rcp_f32_e32 v188, v188
	v_rcp_f32_e32 v189, v189
	v_rcp_f32_e32 v190, v190
	v_rcp_f32_e32 v191, v191
	v_mul_f32_e32 v184, v100, v184
	v_mul_f32_e32 v185, v101, v185
	v_mul_f32_e32 v186, v102, v186
;     __device__ __forceinline__ void operator()(const f32x4 (&acc)[2], int srow, int cgp, int kq) const { one(acc[0], srow, 2 * cgp, kq); one(acc[1], srow, 2 * cgp + 1, kq); }
;     __device__ __forceinline__ void operator()(AccRef acc, const pg8::Unit& u, int wr, int wc, int fr, int fq) const {
;         const int row0 = u.pm * 256 + wr * 64 + fr, col0 = u.pn * 128 + wc * 32 + 8 * fq;
; #pragma unroll
;         for (int ai = 0; ai < 2; ++ai)
; #pragma unroll
;             for (int m = 0; m < 4; ++m) {
;                 const int row = row0 + ai * 128 + m * 16;
;                 const float rs = rs_from(ssp + (size_t)row * 16, 4, 1.0f / 1024.0f);
;                 f32x4 o[2];
; #pragma unroll
;                 for (int n = 0; n < 2; ++n)
; #pragma unroll
;                     for (int j = 0; j < 4; ++j) {
;                         const float g = acc[ai][0][m][n][j] * rs, up = acc[ai][1][m][n][j] * rs;
;                         o[n][j] = g * __builtin_amdgcn_rcpf(1.0f + __expf(-g)) * up;
;                     }
;                 *(u32x4*)(act + (size_t)row * FF + col0) = pack8(o[0], o[1]);
;             }
	v_mul_f32_e32 v187, v103, v187
	v_mul_f32_e32 v188, v96, v188
	v_mul_f32_e32 v189, v97, v189
	v_mul_f32_e32 v190, v98, v190
	v_mul_f32_e32 v191, v99, v191
	v_mul_f32_e32 v184, v108, v184
	v_mul_f32_e32 v185, v109, v185
	v_mul_f32_e32 v186, v110, v186
	v_mul_f32_e32 v187, v111, v187
	v_mul_f32_e32 v188, v104, v188
	v_mul_f32_e32 v189, v105, v189
	v_mul_f32_e32 v190, v106, v190
	v_mul_f32_e32 v191, v107, v191
	v_cvt_pk_bf16_f32 v196, v184, v185
	v_cvt_pk_bf16_f32 v197, v186, v187
	v_cvt_pk_bf16_f32 v198, v188, v189
	v_cvt_pk_bf16_f32 v199, v190, v191
	v_add_u32_e32 v201, 0x16000, v248
	global_store_dwordx4 v201, v[196:199], s[48:49]
	v_pk_mul_f32 v[84:85], v[84:85], v[238:239] op_sel_hi:[1,0]
	v_pk_mul_f32 v[86:87], v[86:87], v[238:239] op_sel_hi:[1,0]
	v_pk_mul_f32 v[80:81], v[80:81], v[238:239] op_sel_hi:[1,0]
	v_pk_mul_f32 v[82:83], v[82:83], v[238:239] op_sel_hi:[1,0]
	v_pk_mul_f32 v[92:93], v[92:93], v[238:239] op_sel_hi:[1,0]
	v_pk_mul_f32 v[94:95], v[94:95], v[238:239] op_sel_hi:[1,0]
	v_pk_mul_f32 v[88:89], v[88:89], v[238:239] op_sel_hi:[1,0]
	v_pk_mul_f32 v[90:91], v[90:91], v[238:239] op_sel_hi:[1,0]
	v_mul_f32_e32 v176, 0xbfb8aa3b, v84
	v_mul_f32_e32 v177, 0xbfb8aa3b, v85
	v_mul_f32_e32 v178, 0xbfb8aa3b, v86
	v_mul_f32_e32 v179, 0xbfb8aa3b, v87
	v_mul_f32_e32 v180, 0xbfb8aa3b, v80
	v_mul_f32_e32 v181, 0xbfb8aa3b, v81
	v_mul_f32_e32 v182, 0xbfb8aa3b, v82
	v_mul_f32_e32 v183, 0xbfb8aa3b, v83
	v_exp_f32_e32 v176, v176
	v_exp_f32_e32 v177, v177
	v_exp_f32_e32 v178, v178
	v_exp_f32_e32 v179, v179
	v_exp_f32_e32 v180, v180
	v_exp_f32_e32 v181, v181
	v_exp_f32_e32 v182, v182
	v_exp_f32_e32 v183, v183
	v_add_f32_e32 v176, 1.0, v176
	v_add_f32_e32 v177, 1.0, v177
	v_add_f32_e32 v178, 1.0, v178
	v_add_f32_e32 v179, 1.0, v179
	v_add_f32_e32 v180, 1.0, v180
	v_add_f32_e32 v181, 1.0, v181
	v_add_f32_e32 v182, 1.0, v182
	v_add_f32_e32 v183, 1.0, v183
	v_rcp_f32_e32 v176, v176
	v_rcp_f32_e32 v177, v177
	v_rcp_f32_e32 v178, v178
	v_rcp_f32_e32 v179, v179
	v_rcp_f32_e32 v180, v180
	v_rcp_f32_e32 v181, v181
	v_rcp_f32_e32 v182, v182
	v_rcp_f32_e32 v183, v183
	v_mul_f32_e32 v176, v84, v176
	v_mul_f32_e32 v177, v85, v177
	v_mul_f32_e32 v178, v86, v178
	v_mul_f32_e32 v179, v87, v179
	v_mul_f32_e32 v180, v80, v180
	v_mul_f32_e32 v181, v81, v181
	v_mul_f32_e32 v182, v82, v182
	v_mul_f32_e32 v183, v83, v183
	v_mul_f32_e32 v176, v92, v176
	v_mul_f32_e32 v177, v93, v177
	v_mul_f32_e32 v178, v94, v178
	v_mul_f32_e32 v179, v95, v179
	v_mul_f32_e32 v180, v88, v180
	v_mul_f32_e32 v181, v89, v181
	v_mul_f32_e32 v182, v90, v182
	v_mul_f32_e32 v183, v91, v183
	v_cvt_pk_bf16_f32 v192, v176, v177
	v_cvt_pk_bf16_f32 v193, v178, v179
	v_cvt_pk_bf16_f32 v194, v180, v181
	v_cvt_pk_bf16_f32 v195, v182, v183
	v_add_u32_e32 v200, 0x2c000, v248
	global_store_dwordx4 v200, v[192:195], s[48:49]
	v_pk_mul_f32 v[68:69], v[68:69], v[242:243] op_sel_hi:[1,0]
	v_pk_mul_f32 v[70:71], v[70:71], v[242:243] op_sel_hi:[1,0]
	v_pk_mul_f32 v[64:65], v[64:65], v[242:243] op_sel_hi:[1,0]
	v_pk_mul_f32 v[66:67], v[66:67], v[242:243] op_sel_hi:[1,0]
	v_pk_mul_f32 v[76:77], v[76:77], v[242:243] op_sel_hi:[1,0]
	v_pk_mul_f32 v[78:79], v[78:79], v[242:243] op_sel_hi:[1,0]
	v_pk_mul_f32 v[72:73], v[72:73], v[242:243] op_sel_hi:[1,0]
	v_pk_mul_f32 v[74:75], v[74:75], v[242:243] op_sel_hi:[1,0]
	v_mul_f32_e32 v184, 0xbfb8aa3b, v68
	v_mul_f32_e32 v185, 0xbfb8aa3b, v69
	v_mul_f32_e32 v186, 0xbfb8aa3b, v70
	v_mul_f32_e32 v187, 0xbfb8aa3b, v71
	v_mul_f32_e32 v188, 0xbfb8aa3b, v64
	v_mul_f32_e32 v189, 0xbfb8aa3b, v65
	v_mul_f32_e32 v190, 0xbfb8aa3b, v66
	v_mul_f32_e32 v191, 0xbfb8aa3b, v67
	v_exp_f32_e32 v184, v184
	v_exp_f32_e32 v185, v185
	v_exp_f32_e32 v186, v186
	v_exp_f32_e32 v187, v187
	v_exp_f32_e32 v188, v188
	v_exp_f32_e32 v189, v189
	v_exp_f32_e32 v190, v190
	v_exp_f32_e32 v191, v191
	v_add_f32_e32 v184, 1.0, v184
	v_add_f32_e32 v185, 1.0, v185
	v_add_f32_e32 v186, 1.0, v186
	v_add_f32_e32 v187, 1.0, v187
	v_add_f32_e32 v188, 1.0, v188
	v_add_f32_e32 v189, 1.0, v189
	v_add_f32_e32 v190, 1.0, v190
	v_add_f32_e32 v191, 1.0, v191
	v_rcp_f32_e32 v184, v184
	v_rcp_f32_e32 v185, v185
	v_rcp_f32_e32 v186, v186
	v_rcp_f32_e32 v187, v187
	v_rcp_f32_e32 v188, v188
	v_rcp_f32_e32 v189, v189
	v_rcp_f32_e32 v190, v190
	v_rcp_f32_e32 v191, v191
	v_mul_f32_e32 v184, v68, v184
	v_mul_f32_e32 v185, v69, v185
	v_mul_f32_e32 v186, v70, v186
	v_mul_f32_e32 v187, v71, v187
	v_mul_f32_e32 v188, v64, v188
	v_mul_f32_e32 v189, v65, v189
	v_mul_f32_e32 v190, v66, v190
	v_mul_f32_e32 v191, v67, v191
	v_mul_f32_e32 v184, v76, v184
	v_mul_f32_e32 v185, v77, v185
	v_mul_f32_e32 v186, v78, v186
	v_mul_f32_e32 v187, v79, v187
	v_mul_f32_e32 v188, v72, v188
	v_mul_f32_e32 v189, v73, v189
	v_mul_f32_e32 v190, v74, v190
	v_mul_f32_e32 v191, v75, v191
	v_cvt_pk_bf16_f32 v196, v184, v185
	v_cvt_pk_bf16_f32 v197, v186, v187
	v_cvt_pk_bf16_f32 v198, v188, v189
	v_cvt_pk_bf16_f32 v199, v190, v191
	v_add_u32_e32 v201, 0x42000, v248
	global_store_dwordx4 v201, v[196:199], s[48:49]
	s_waitcnt vmcnt(4)
	v_add_f32_e32 v154, v154, v155
	v_add_f32_e32 v156, v156, v157
	v_add_f32_e32 v158, v158, v159
	v_add_f32_e32 v160, v160, v161
	v_add_f32_e32 v162, v162, v163
	v_add_f32_e32 v164, v164, v165
	v_add_f32_e32 v166, v166, v167
	v_add_f32_e32 v168, v168, v169
	v_add_f32_e32 v154, v154, v156
	v_add_f32_e32 v158, v158, v160
	v_add_f32_e32 v162, v162, v164
	v_add_f32_e32 v166, v166, v168
	ds_bpermute_b32 v155, v171, v154
	ds_bpermute_b32 v159, v171, v158
	ds_bpermute_b32 v163, v171, v162
	ds_bpermute_b32 v167, v171, v166
	s_waitcnt lgkmcnt(0)
;     __device__ __forceinline__ void operator()(const f32x4 (&acc)[2], int srow, int cgp, int kq) const { one(acc[0], srow, 2 * cgp, kq); one(acc[1], srow, 2 * cgp + 1, kq); }
;     __device__ __forceinline__ void operator()(AccRef acc, const pg8::Unit& u, int wr, int wc, int fr, int fq) const {
;         const int row0 = u.pm * 256 + wr * 64 + fr, col0 = u.pn * 128 + wc * 32 + 8 * fq;
; #pragma unroll
;         for (int ai = 0; ai < 2; ++ai)
; #pragma unroll
;             for (int m = 0; m < 4; ++m) {
;                 const int row = row0 + ai * 128 + m * 16;
;                 const float rs = rs_from(ssp + (size_t)row * 16, 4, 1.0f / 1024.0f);
;                 f32x4 o[2];
; #pragma unroll
;                 for (int n = 0; n < 2; ++n)
; #pragma unroll
;                     for (int j = 0; j < 4; ++j) {
;                         const float g = acc[ai][0][m][n][j] * rs, up = acc[ai][1][m][n][j] * rs;
;                         o[n][j] = g * __builtin_amdgcn_rcpf(1.0f + __expf(-g)) * up;
;                     }
;                 *(u32x4*)(act + (size_t)row * FF + col0) = pack8(o[0], o[1]);
;             }
	v_add_f32_e32 v154, v154, v155
	v_add_f32_e32 v158, v158, v159
	v_add_f32_e32 v162, v162, v163
	v_add_f32_e32 v166, v166, v167
	ds_bpermute_b32 v155, v172, v154
	ds_bpermute_b32 v159, v172, v158
	ds_bpermute_b32 v163, v172, v162
	ds_bpermute_b32 v167, v172, v166
	s_waitcnt lgkmcnt(0)
	v_add_f32_e32 v154, v154, v155
	v_add_f32_e32 v158, v158, v159
	v_add_f32_e32 v162, v162, v163
	v_add_f32_e32 v166, v166, v167
	v_fmamk_f32 v154, v154, 0x3a800000, v152
	v_fmamk_f32 v158, v158, 0x3a800000, v152
	v_fmamk_f32 v162, v162, 0x3a800000, v152
	v_fmamk_f32 v166, v166, 0x3a800000, v152
	v_rsq_f32_e32 v154, v154
	v_rsq_f32_e32 v158, v158
	v_rsq_f32_e32 v162, v162
	v_rsq_f32_e32 v166, v166
	s_nop 0
	v_pk_mul_f32 v[52:53], v[52:53], v[154:155] op_sel_hi:[1,0]
	v_pk_mul_f32 v[54:55], v[54:55], v[154:155] op_sel_hi:[1,0]
	v_pk_mul_f32 v[48:49], v[48:49], v[154:155] op_sel_hi:[1,0]
	v_pk_mul_f32 v[50:51], v[50:51], v[154:155] op_sel_hi:[1,0]
	v_pk_mul_f32 v[60:61], v[60:61], v[154:155] op_sel_hi:[1,0]
	v_pk_mul_f32 v[62:63], v[62:63], v[154:155] op_sel_hi:[1,0]
	v_pk_mul_f32 v[56:57], v[56:57], v[154:155] op_sel_hi:[1,0]
	v_pk_mul_f32 v[58:59], v[58:59], v[154:155] op_sel_hi:[1,0]
	v_mul_f32_e32 v176, 0xbfb8aa3b, v52
	v_mul_f32_e32 v177, 0xbfb8aa3b, v53
	v_mul_f32_e32 v178, 0xbfb8aa3b, v54
	v_mul_f32_e32 v179, 0xbfb8aa3b, v55
	v_mul_f32_e32 v180, 0xbfb8aa3b, v48
	v_mul_f32_e32 v181, 0xbfb8aa3b, v49
	v_mul_f32_e32 v182, 0xbfb8aa3b, v50
	v_mul_f32_e32 v183, 0xbfb8aa3b, v51
	v_exp_f32_e32 v176, v176
	v_exp_f32_e32 v177, v177
	v_exp_f32_e32 v178, v178
	v_exp_f32_e32 v179, v179
	v_exp_f32_e32 v180, v180
	v_exp_f32_e32 v181, v181
	v_exp_f32_e32 v182, v182
	v_exp_f32_e32 v183, v183
	v_add_f32_e32 v176, 1.0, v176
	v_add_f32_e32 v177, 1.0, v177
	v_add_f32_e32 v178, 1.0, v178
	v_add_f32_e32 v179, 1.0, v179
	v_add_f32_e32 v180, 1.0, v180
	v_add_f32_e32 v181, 1.0, v181
	v_add_f32_e32 v182, 1.0, v182
	v_add_f32_e32 v183, 1.0, v183
	v_rcp_f32_e32 v176, v176
	v_rcp_f32_e32 v177, v177
	v_rcp_f32_e32 v178, v178
	v_rcp_f32_e32 v179, v179
	v_rcp_f32_e32 v180, v180
	v_rcp_f32_e32 v181, v181
	v_rcp_f32_e32 v182, v182
	v_rcp_f32_e32 v183, v183
	v_mul_f32_e32 v176, v52, v176
	v_mul_f32_e32 v177, v53, v177
	v_mul_f32_e32 v178, v54, v178
	v_mul_f32_e32 v179, v55, v179
	v_mul_f32_e32 v180, v48, v180
	v_mul_f32_e32 v181, v49, v181
	v_mul_f32_e32 v182, v50, v182
	v_mul_f32_e32 v183, v51, v183
	v_mul_f32_e32 v176, v60, v176
	v_mul_f32_e32 v177, v61, v177
	v_mul_f32_e32 v178, v62, v178
	v_mul_f32_e32 v179, v63, v179
	v_mul_f32_e32 v180, v56, v180
	v_mul_f32_e32 v181, v57, v181
	v_mul_f32_e32 v182, v58, v182
	v_mul_f32_e32 v183, v59, v183
	v_cvt_pk_bf16_f32 v192, v176, v177
	v_cvt_pk_bf16_f32 v193, v178, v179
	v_cvt_pk_bf16_f32 v194, v180, v181
	v_cvt_pk_bf16_f32 v195, v182, v183
	v_add_u32_e32 v200, 0xb0000, v248
	global_store_dwordx4 v200, v[192:195], s[48:49]
	v_pk_mul_f32 v[36:37], v[36:37], v[158:159] op_sel_hi:[1,0]
	v_pk_mul_f32 v[38:39], v[38:39], v[158:159] op_sel_hi:[1,0]
	v_pk_mul_f32 v[32:33], v[32:33], v[158:159] op_sel_hi:[1,0]
	v_pk_mul_f32 v[34:35], v[34:35], v[158:159] op_sel_hi:[1,0]
	v_pk_mul_f32 v[44:45], v[44:45], v[158:159] op_sel_hi:[1,0]
	v_pk_mul_f32 v[46:47], v[46:47], v[158:159] op_sel_hi:[1,0]
	v_pk_mul_f32 v[40:41], v[40:41], v[158:159] op_sel_hi:[1,0]
	v_pk_mul_f32 v[42:43], v[42:43], v[158:159] op_sel_hi:[1,0]
	v_mul_f32_e32 v184, 0xbfb8aa3b, v36
	v_mul_f32_e32 v185, 0xbfb8aa3b, v37
	v_mul_f32_e32 v186, 0xbfb8aa3b, v38
	v_mul_f32_e32 v187, 0xbfb8aa3b, v39
	v_mul_f32_e32 v188, 0xbfb8aa3b, v32
	v_mul_f32_e32 v189, 0xbfb8aa3b, v33
	v_mul_f32_e32 v190, 0xbfb8aa3b, v34
	v_mul_f32_e32 v191, 0xbfb8aa3b, v35
	v_exp_f32_e32 v184, v184
	v_exp_f32_e32 v185, v185
	v_exp_f32_e32 v186, v186
	v_exp_f32_e32 v187, v187
	v_exp_f32_e32 v188, v188
	v_exp_f32_e32 v189, v189
	v_exp_f32_e32 v190, v190
	v_exp_f32_e32 v191, v191
	v_add_f32_e32 v184, 1.0, v184
	v_add_f32_e32 v185, 1.0, v185
	v_add_f32_e32 v186, 1.0, v186
	v_add_f32_e32 v187, 1.0, v187
	v_add_f32_e32 v188, 1.0, v188
	v_add_f32_e32 v189, 1.0, v189
	v_add_f32_e32 v190, 1.0, v190
	v_add_f32_e32 v191, 1.0, v191
	v_rcp_f32_e32 v184, v184
	v_rcp_f32_e32 v185, v185
	v_rcp_f32_e32 v186, v186
	v_rcp_f32_e32 v187, v187
	v_rcp_f32_e32 v188, v188
	v_rcp_f32_e32 v189, v189
	v_rcp_f32_e32 v190, v190
	v_rcp_f32_e32 v191, v191
	v_mul_f32_e32 v184, v36, v184
	v_mul_f32_e32 v185, v37, v185
	v_mul_f32_e32 v186, v38, v186
	v_mul_f32_e32 v187, v39, v187
	v_mul_f32_e32 v188, v32, v188
	v_mul_f32_e32 v189, v33, v189
	v_mul_f32_e32 v190, v34, v190
	v_mul_f32_e32 v191, v35, v191
	v_mul_f32_e32 v184, v44, v184
	v_mul_f32_e32 v185, v45, v185
	v_mul_f32_e32 v186, v46, v186
	v_mul_f32_e32 v187, v47, v187
	v_mul_f32_e32 v188, v40, v188
	v_mul_f32_e32 v189, v41, v189
;     __device__ __forceinline__ void operator()(const f32x4 (&acc)[2], int srow, int cgp, int kq) const { one(acc[0], srow, 2 * cgp, kq); one(acc[1], srow, 2 * cgp + 1, kq); }
;     __device__ __forceinline__ void operator()(AccRef acc, const pg8::Unit& u, int wr, int wc, int fr, int fq) const {
;         const int row0 = u.pm * 256 + wr * 64 + fr, col0 = u.pn * 128 + wc * 32 + 8 * fq;
; #pragma unroll
;         for (int ai = 0; ai < 2; ++ai)
; #pragma unroll
;             for (int m = 0; m < 4; ++m) {
;                 const int row = row0 + ai * 128 + m * 16;
;                 const float rs = rs_from(ssp + (size_t)row * 16, 4, 1.0f / 1024.0f);
;                 f32x4 o[2];
; #pragma unroll
;                 for (int n = 0; n < 2; ++n)
; #pragma unroll
;                     for (int j = 0; j < 4; ++j) {
;                         const float g = acc[ai][0][m][n][j] * rs, up = acc[ai][1][m][n][j] * rs;
;                         o[n][j] = g * __builtin_amdgcn_rcpf(1.0f + __expf(-g)) * up;
;                     }
;                 *(u32x4*)(act + (size_t)row * FF + col0) = pack8(o[0], o[1]);
;             }
	v_mul_f32_e32 v190, v42, v190
	v_mul_f32_e32 v191, v43, v191
	v_cvt_pk_bf16_f32 v196, v184, v185
	v_cvt_pk_bf16_f32 v197, v186, v187
	v_cvt_pk_bf16_f32 v198, v188, v189
	v_cvt_pk_bf16_f32 v199, v190, v191
	v_add_u32_e32 v201, 0xc6000, v248
	global_store_dwordx4 v201, v[196:199], s[48:49]
	v_pk_mul_f32 v[20:21], v[20:21], v[162:163] op_sel_hi:[1,0]
	v_pk_mul_f32 v[22:23], v[22:23], v[162:163] op_sel_hi:[1,0]
	v_pk_mul_f32 v[16:17], v[16:17], v[162:163] op_sel_hi:[1,0]
	v_pk_mul_f32 v[18:19], v[18:19], v[162:163] op_sel_hi:[1,0]
	v_pk_mul_f32 v[28:29], v[28:29], v[162:163] op_sel_hi:[1,0]
	v_pk_mul_f32 v[30:31], v[30:31], v[162:163] op_sel_hi:[1,0]
	v_pk_mul_f32 v[24:25], v[24:25], v[162:163] op_sel_hi:[1,0]
	v_pk_mul_f32 v[26:27], v[26:27], v[162:163] op_sel_hi:[1,0]
	v_mul_f32_e32 v176, 0xbfb8aa3b, v20
	v_mul_f32_e32 v177, 0xbfb8aa3b, v21
	v_mul_f32_e32 v178, 0xbfb8aa3b, v22
	v_mul_f32_e32 v179, 0xbfb8aa3b, v23
	v_mul_f32_e32 v180, 0xbfb8aa3b, v16
	v_mul_f32_e32 v181, 0xbfb8aa3b, v17
	v_mul_f32_e32 v182, 0xbfb8aa3b, v18
	v_mul_f32_e32 v183, 0xbfb8aa3b, v19
	v_exp_f32_e32 v176, v176
	v_exp_f32_e32 v177, v177
	v_exp_f32_e32 v178, v178
	v_exp_f32_e32 v179, v179
	v_exp_f32_e32 v180, v180
	v_exp_f32_e32 v181, v181
	v_exp_f32_e32 v182, v182
	v_exp_f32_e32 v183, v183
	v_add_f32_e32 v176, 1.0, v176
	v_add_f32_e32 v177, 1.0, v177
	v_add_f32_e32 v178, 1.0, v178
	v_add_f32_e32 v179, 1.0, v179
	v_add_f32_e32 v180, 1.0, v180
	v_add_f32_e32 v181, 1.0, v181
	v_add_f32_e32 v182, 1.0, v182
	v_add_f32_e32 v183, 1.0, v183
	v_rcp_f32_e32 v176, v176
	v_rcp_f32_e32 v177, v177
	v_rcp_f32_e32 v178, v178
	v_rcp_f32_e32 v179, v179
	v_rcp_f32_e32 v180, v180
	v_rcp_f32_e32 v181, v181
	v_rcp_f32_e32 v182, v182
	v_rcp_f32_e32 v183, v183
	v_mul_f32_e32 v176, v20, v176
	v_mul_f32_e32 v177, v21, v177
	v_mul_f32_e32 v178, v22, v178
	v_mul_f32_e32 v179, v23, v179
	v_mul_f32_e32 v180, v16, v180
	v_mul_f32_e32 v181, v17, v181
	v_mul_f32_e32 v182, v18, v182
	v_mul_f32_e32 v183, v19, v183
	v_mul_f32_e32 v176, v28, v176
	v_mul_f32_e32 v177, v29, v177
	v_mul_f32_e32 v178, v30, v178
	v_mul_f32_e32 v179, v31, v179
	v_mul_f32_e32 v180, v24, v180
	v_mul_f32_e32 v181, v25, v181
	v_mul_f32_e32 v182, v26, v182
	v_mul_f32_e32 v183, v27, v183
	v_cvt_pk_bf16_f32 v192, v176, v177
	v_cvt_pk_bf16_f32 v193, v178, v179
	v_cvt_pk_bf16_f32 v194, v180, v181
	v_cvt_pk_bf16_f32 v195, v182, v183
	v_add_u32_e32 v200, 0xdc000, v248
	global_store_dwordx4 v200, v[192:195], s[48:49]
	v_pk_mul_f32 v[4:5], v[4:5], v[166:167] op_sel_hi:[1,0]
	v_pk_mul_f32 v[6:7], v[6:7], v[166:167] op_sel_hi:[1,0]
	v_pk_mul_f32 v[0:1], v[0:1], v[166:167] op_sel_hi:[1,0]
	v_pk_mul_f32 v[2:3], v[2:3], v[166:167] op_sel_hi:[1,0]
	v_pk_mul_f32 v[12:13], v[12:13], v[166:167] op_sel_hi:[1,0]
	v_pk_mul_f32 v[14:15], v[14:15], v[166:167] op_sel_hi:[1,0]
	v_pk_mul_f32 v[8:9], v[8:9], v[166:167] op_sel_hi:[1,0]
	v_pk_mul_f32 v[10:11], v[10:11], v[166:167] op_sel_hi:[1,0]
	v_mul_f32_e32 v184, 0xbfb8aa3b, v4
	v_mul_f32_e32 v185, 0xbfb8aa3b, v5
	v_mul_f32_e32 v186, 0xbfb8aa3b, v6
	v_mul_f32_e32 v187, 0xbfb8aa3b, v7
	v_mul_f32_e32 v188, 0xbfb8aa3b, v0
	v_mul_f32_e32 v189, 0xbfb8aa3b, v1
	v_mul_f32_e32 v190, 0xbfb8aa3b, v2
	v_mul_f32_e32 v191, 0xbfb8aa3b, v3
	v_exp_f32_e32 v184, v184
	v_exp_f32_e32 v185, v185
	v_exp_f32_e32 v186, v186
	v_exp_f32_e32 v187, v187
	v_exp_f32_e32 v188, v188
	v_exp_f32_e32 v189, v189
	v_exp_f32_e32 v190, v190
	v_exp_f32_e32 v191, v191
	v_add_f32_e32 v184, 1.0, v184
	v_add_f32_e32 v185, 1.0, v185
	v_add_f32_e32 v186, 1.0, v186
	v_add_f32_e32 v187, 1.0, v187
	v_add_f32_e32 v188, 1.0, v188
	v_add_f32_e32 v189, 1.0, v189
	v_add_f32_e32 v190, 1.0, v190
	v_add_f32_e32 v191, 1.0, v191
	v_rcp_f32_e32 v184, v184
	v_rcp_f32_e32 v185, v185
	v_rcp_f32_e32 v186, v186
	v_rcp_f32_e32 v187, v187
	v_rcp_f32_e32 v188, v188
	v_rcp_f32_e32 v189, v189
	v_rcp_f32_e32 v190, v190
	v_rcp_f32_e32 v191, v191
	v_mul_f32_e32 v184, v4, v184
	v_mul_f32_e32 v185, v5, v185
	v_mul_f32_e32 v186, v6, v186
	v_mul_f32_e32 v187, v7, v187
	v_mul_f32_e32 v188, v0, v188
	v_mul_f32_e32 v189, v1, v189
	v_mul_f32_e32 v190, v2, v190
	v_mul_f32_e32 v191, v3, v191
	v_mul_f32_e32 v184, v12, v184
	v_mul_f32_e32 v185, v13, v185
	v_mul_f32_e32 v186, v14, v186
	v_mul_f32_e32 v187, v15, v187
	v_mul_f32_e32 v188, v8, v188
	v_mul_f32_e32 v189, v9, v189
	v_mul_f32_e32 v190, v10, v190
	v_mul_f32_e32 v191, v11, v191
	v_cvt_pk_bf16_f32 v196, v184, v185
	v_cvt_pk_bf16_f32 v197, v186, v187
	v_cvt_pk_bf16_f32 v198, v188, v189
	v_cvt_pk_bf16_f32 v199, v190, v191
	v_add_u32_e32 v201, 0xf2000, v248
	global_store_dwordx4 v201, v[196:199], s[48:49]
.Lswi_end1:
	s_and_b64 vcc, exec, s[2:3]
	s_mov_b64 s[2:3], -1
	s_cbranch_vccnz .LBB0_1308
	s_andn2_b64 vcc, exec, s[12:13]
	s_cbranch_vccnz .LBB0_1307
	s_barrier
	s_branch .LBB0_1307

;     __device__ __forceinline__ void operator()(const f32x4 (&acc)[2], int srow, int cgp, int kq) const { one(acc[0], srow, 2 * cgp, kq); one(acc[1], srow, 2 * cgp + 1, kq); }
;     __device__ __forceinline__ void operator()(AccRef acc, const pg8::Unit& u, int wr, int wc, int fr, int fq) const {
;         const int row0 = u.pm * 256 + wr * 64 + fr, col0 = u.pn * 128 + wc * 32 + 8 * fq;
; #pragma unroll
;         for (int ai = 0; ai < 2; ++ai)
; #pragma unroll
;             for (int m = 0; m < 4; ++m) {
;                 const int row = row0 + ai * 128 + m * 16;
;                 const float rs = rs_from(ssp + (size_t)row * 16, 4, 1.0f / 1024.0f);
;                 f32x4 o[2];
; #pragma unroll
;                 for (int n = 0; n < 2; ++n)
; #pragma unroll
;                     for (int j = 0; j < 4; ++j) {
;                         const float g = acc[ai][0][m][n][j] * rs, up = acc[ai][1][m][n][j] * rs;
;                         o[n][j] = g * __builtin_amdgcn_rcpf(1.0f + __expf(-g)) * up;
;                     }
;                 *(u32x4*)(act + (size_t)row * FF + col0) = pack8(o[0], o[1]);
;             }
.LBB0_2484:
.Lswi_beg3:
	v_add_u32_e32 v249, 0x2000, v247
	global_load_dwordx4 v[154:157], v249, s[46:47]
	global_load_dwordx4 v[158:161], v249, s[46:47] offset:1024
	global_load_dwordx4 v[162:165], v249, s[46:47] offset:2048
	global_load_dwordx4 v[166:169], v249, s[46:47] offset:3072
	v_mbcnt_lo_u32_b32 v170, -1, 0
	v_mbcnt_hi_u32_b32 v170, -1, v170
	v_xor_b32_e32 v171, 16, v170
	v_xor_b32_e32 v172, 32, v170
	v_lshlrev_b32_e32 v171, 2, v171
	v_lshlrev_b32_e32 v172, 2, v172
	v_lshl_or_b32 v173, s59, 7, v148
	v_lshlrev_b32_e32 v173, 1, v173
	v_mad_u32_u24 v248, v246, s51, v173
	s_waitcnt vmcnt(12)
	v_add_f32_e32 v230, v230, v231
	v_add_f32_e32 v232, v232, v233
	v_add_f32_e32 v234, v234, v235
	v_add_f32_e32 v236, v236, v237
	v_add_f32_e32 v238, v238, v239
	v_add_f32_e32 v240, v240, v241
	v_add_f32_e32 v242, v242, v243
	v_add_f32_e32 v244, v244, v245
	v_add_f32_e32 v230, v230, v232
	v_add_f32_e32 v234, v234, v236
	v_add_f32_e32 v238, v238, v240
	v_add_f32_e32 v242, v242, v244
	ds_bpermute_b32 v231, v171, v230
	ds_bpermute_b32 v235, v171, v234
	ds_bpermute_b32 v239, v171, v238
	ds_bpermute_b32 v243, v171, v242
	s_waitcnt lgkmcnt(0)
	v_add_f32_e32 v230, v230, v231
	v_add_f32_e32 v234, v234, v235
	v_add_f32_e32 v238, v238, v239
	v_add_f32_e32 v242, v242, v243
	ds_bpermute_b32 v231, v172, v230
	ds_bpermute_b32 v235, v172, v234
	ds_bpermute_b32 v239, v172, v238
	ds_bpermute_b32 v243, v172, v242
	s_waitcnt lgkmcnt(0)
	v_add_f32_e32 v230, v230, v231
	v_add_f32_e32 v234, v234, v235
	v_add_f32_e32 v238, v238, v239
	v_add_f32_e32 v242, v242, v243
	v_fmamk_f32 v230, v230, 0x3a800000, v152
	v_fmamk_f32 v234, v234, 0x3a800000, v152
	v_fmamk_f32 v238, v238, 0x3a800000, v152
	v_fmamk_f32 v242, v242, 0x3a800000, v152
	v_rsq_f32_e32 v230, v230
	v_rsq_f32_e32 v234, v234
	v_rsq_f32_e32 v238, v238
	v_rsq_f32_e32 v242, v242
	s_nop 0
	v_pk_mul_f32 v[116:117], v[116:117], v[230:231] op_sel_hi:[1,0]
	v_pk_mul_f32 v[118:119], v[118:119], v[230:231] op_sel_hi:[1,0]
	v_pk_mul_f32 v[112:113], v[112:113], v[230:231] op_sel_hi:[1,0]
	v_pk_mul_f32 v[114:115], v[114:115], v[230:231] op_sel_hi:[1,0]
	v_pk_mul_f32 v[124:125], v[124:125], v[230:231] op_sel_hi:[1,0]
	v_pk_mul_f32 v[126:127], v[126:127], v[230:231] op_sel_hi:[1,0]
	v_pk_mul_f32 v[120:121], v[120:121], v[230:231] op_sel_hi:[1,0]
	v_pk_mul_f32 v[122:123], v[122:123], v[230:231] op_sel_hi:[1,0]
	v_mul_f32_e32 v176, 0xbfb8aa3b, v116
	v_mul_f32_e32 v177, 0xbfb8aa3b, v117
	v_mul_f32_e32 v178, 0xbfb8aa3b, v118
	v_mul_f32_e32 v179, 0xbfb8aa3b, v119
	v_mul_f32_e32 v180, 0xbfb8aa3b, v112
	v_mul_f32_e32 v181, 0xbfb8aa3b, v113
	v_mul_f32_e32 v182, 0xbfb8aa3b, v114
	v_mul_f32_e32 v183, 0xbfb8aa3b, v115
	v_exp_f32_e32 v176, v176
	v_exp_f32_e32 v177, v177
	v_exp_f32_e32 v178, v178
	v_exp_f32_e32 v179, v179
	v_exp_f32_e32 v180, v180
	v_exp_f32_e32 v181, v181
	v_exp_f32_e32 v182, v182
	v_exp_f32_e32 v183, v183
	v_add_f32_e32 v176, 1.0, v176
	v_add_f32_e32 v177, 1.0, v177
	v_add_f32_e32 v178, 1.0, v178
	v_add_f32_e32 v179, 1.0, v179
	v_add_f32_e32 v180, 1.0, v180
	v_add_f32_e32 v181, 1.0, v181
	v_add_f32_e32 v182, 1.0, v182
	v_add_f32_e32 v183, 1.0, v183
	v_rcp_f32_e32 v176, v176
	v_rcp_f32_e32 v177, v177
	v_rcp_f32_e32 v178, v178
	v_rcp_f32_e32 v179, v179
	v_rcp_f32_e32 v180, v180
	v_rcp_f32_e32 v181, v181
	v_rcp_f32_e32 v182, v182
	v_rcp_f32_e32 v183, v183
	v_mul_f32_e32 v176, v116, v176
	v_mul_f32_e32 v177, v117, v177
	v_mul_f32_e32 v178, v118, v178
	v_mul_f32_e32 v179, v119, v179
	v_mul_f32_e32 v180, v112, v180
	v_mul_f32_e32 v181, v113, v181
	v_mul_f32_e32 v182, v114, v182
	v_mul_f32_e32 v183, v115, v183
	v_mul_f32_e32 v176, v124, v176
	v_mul_f32_e32 v177, v125, v177
	v_mul_f32_e32 v178, v126, v178
	v_mul_f32_e32 v179, v127, v179
	v_mul_f32_e32 v180, v120, v180
	v_mul_f32_e32 v181, v121, v181
	v_mul_f32_e32 v182, v122, v182
	v_mul_f32_e32 v183, v123, v183
	v_cvt_pk_bf16_f32 v192, v176, v177
	v_cvt_pk_bf16_f32 v193, v178, v179
	v_cvt_pk_bf16_f32 v194, v180, v181
	v_cvt_pk_bf16_f32 v195, v182, v183
	v_mov_b32_e32 v200, v248
	global_store_dwordx4 v200, v[192:195], s[48:49]
	v_pk_mul_f32 v[100:101], v[100:101], v[234:235] op_sel_hi:[1,0]
	v_pk_mul_f32 v[102:103], v[102:103], v[234:235] op_sel_hi:[1,0]
	v_pk_mul_f32 v[96:97], v[96:97], v[234:235] op_sel_hi:[1,0]
	v_pk_mul_f32 v[98:99], v[98:99], v[234:235] op_sel_hi:[1,0]
	v_pk_mul_f32 v[108:109], v[108:109], v[234:235] op_sel_hi:[1,0]
	v_pk_mul_f32 v[110:111], v[110:111], v[234:235] op_sel_hi:[1,0]
	v_pk_mul_f32 v[104:105], v[104:105], v[234:235] op_sel_hi:[1,0]
	v_pk_mul_f32 v[106:107], v[106:107], v[234:235] op_sel_hi:[1,0]
	v_mul_f32_e32 v184, 0xbfb8aa3b, v100
	v_mul_f32_e32 v185, 0xbfb8aa3b, v101
	v_mul_f32_e32 v186, 0xbfb8aa3b, v102
	v_mul_f32_e32 v187, 0xbfb8aa3b, v103
	v_mul_f32_e32 v188, 0xbfb8aa3b, v96
	v_mul_f32_e32 v189, 0xbfb8aa3b, v97
	v_mul_f32_e32 v190, 0xbfb8aa3b, v98
	v_mul_f32_e32 v191, 0xbfb8aa3b, v99
	v_exp_f32_e32 v184, v184
	v_exp_f32_e32 v185, v185
	v_exp_f32_e32 v186, v186
	v_exp_f32_e32 v187, v187
	v_exp_f32_e32 v188, v188
	v_exp_f32_e32 v189, v189
	v_exp_f32_e32 v190, v190
	v_exp_f32_e32 v191, v191
	v_add_f32_e32 v184, 1.0, v184
	v_add_f32_e32 v185, 1.0, v185
	v_add_f32_e32 v186, 1.0, v186
	v_add_f32_e32 v187, 1.0, v187
	v_add_f32_e32 v188, 1.0, v188
	v_add_f32_e32 v189, 1.0, v189
	v_add_f32_e32 v190, 1.0, v190
	v_add_f32_e32 v191, 1.0, v191
	v_rcp_f32_e32 v184, v184
	v_rcp_f32_e32 v185, v185
	v_rcp_f32_e32 v186, v186
	v_rcp_f32_e32 v187, v187
	v_rcp_f32_e32 v188, v188
	v_rcp_f32_e32 v189, v189
	v_rcp_f32_e32 v190, v190
	v_rcp_f32_e32 v191, v191
	v_mul_f32_e32 v184, v100, v184
	v_mul_f32_e32 v185, v101, v185
	v_mul_f32_e32 v186, v102, v186
;     __device__ __forceinline__ void operator()(const f32x4 (&acc)[2], int srow, int cgp, int kq) const { one(acc[0], srow, 2 * cgp, kq); one(acc[1], srow, 2 * cgp + 1, kq); }
;     __device__ __forceinline__ void operator()(AccRef acc, const pg8::Unit& u, int wr, int wc, int fr, int fq) const {
;         const int row0 = u.pm * 256 + wr * 64 + fr, col0 = u.pn * 128 + wc * 32 + 8 * fq;
; #pragma unroll
;         for (int ai = 0; ai < 2; ++ai)
; #pragma unroll
;             for (int m = 0; m < 4; ++m) {
;                 const int row = row0 + ai * 128 + m * 16;
;                 const float rs = rs_from(ssp + (size_t)row * 16, 4, 1.0f / 1024.0f);
;                 f32x4 o[2];
; #pragma unroll
;                 for (int n = 0; n < 2; ++n)
; #pragma unroll
;                     for (int j = 0; j < 4; ++j) {
;                         const float g = acc[ai][0][m][n][j] * rs, up = acc[ai][1][m][n][j] * rs;
;                         o[n][j] = g * __builtin_amdgcn_rcpf(1.0f + __expf(-g)) * up;
;                     }
;                 *(u32x4*)(act + (size_t)row * FF + col0) = pack8(o[0], o[1]);
;             }
	v_mul_f32_e32 v187, v103, v187
	v_mul_f32_e32 v188, v96, v188
	v_mul_f32_e32 v189, v97, v189
	v_mul_f32_e32 v190, v98, v190
	v_mul_f32_e32 v191, v99, v191
	v_mul_f32_e32 v184, v108, v184
	v_mul_f32_e32 v185, v109, v185
	v_mul_f32_e32 v186, v110, v186
	v_mul_f32_e32 v187, v111, v187
	v_mul_f32_e32 v188, v104, v188
	v_mul_f32_e32 v189, v105, v189
	v_mul_f32_e32 v190, v106, v190
	v_mul_f32_e32 v191, v107, v191
	v_cvt_pk_bf16_f32 v196, v184, v185
	v_cvt_pk_bf16_f32 v197, v186, v187
	v_cvt_pk_bf16_f32 v198, v188, v189
	v_cvt_pk_bf16_f32 v199, v190, v191
	v_add_u32_e32 v201, 0x16000, v248
	global_store_dwordx4 v201, v[196:199], s[48:49]
	v_pk_mul_f32 v[84:85], v[84:85], v[238:239] op_sel_hi:[1,0]
	v_pk_mul_f32 v[86:87], v[86:87], v[238:239] op_sel_hi:[1,0]
	v_pk_mul_f32 v[80:81], v[80:81], v[238:239] op_sel_hi:[1,0]
	v_pk_mul_f32 v[82:83], v[82:83], v[238:239] op_sel_hi:[1,0]
	v_pk_mul_f32 v[92:93], v[92:93], v[238:239] op_sel_hi:[1,0]
	v_pk_mul_f32 v[94:95], v[94:95], v[238:239] op_sel_hi:[1,0]
	v_pk_mul_f32 v[88:89], v[88:89], v[238:239] op_sel_hi:[1,0]
	v_pk_mul_f32 v[90:91], v[90:91], v[238:239] op_sel_hi:[1,0]
	v_mul_f32_e32 v176, 0xbfb8aa3b, v84
	v_mul_f32_e32 v177, 0xbfb8aa3b, v85
	v_mul_f32_e32 v178, 0xbfb8aa3b, v86
	v_mul_f32_e32 v179, 0xbfb8aa3b, v87
	v_mul_f32_e32 v180, 0xbfb8aa3b, v80
	v_mul_f32_e32 v181, 0xbfb8aa3b, v81
	v_mul_f32_e32 v182, 0xbfb8aa3b, v82
	v_mul_f32_e32 v183, 0xbfb8aa3b, v83
	v_exp_f32_e32 v176, v176
	v_exp_f32_e32 v177, v177
	v_exp_f32_e32 v178, v178
	v_exp_f32_e32 v179, v179
	v_exp_f32_e32 v180, v180
	v_exp_f32_e32 v181, v181
	v_exp_f32_e32 v182, v182
	v_exp_f32_e32 v183, v183
	v_add_f32_e32 v176, 1.0, v176
	v_add_f32_e32 v177, 1.0, v177
	v_add_f32_e32 v178, 1.0, v178
	v_add_f32_e32 v179, 1.0, v179
	v_add_f32_e32 v180, 1.0, v180
	v_add_f32_e32 v181, 1.0, v181
	v_add_f32_e32 v182, 1.0, v182
	v_add_f32_e32 v183, 1.0, v183
	v_rcp_f32_e32 v176, v176
	v_rcp_f32_e32 v177, v177
	v_rcp_f32_e32 v178, v178
	v_rcp_f32_e32 v179, v179
	v_rcp_f32_e32 v180, v180
	v_rcp_f32_e32 v181, v181
	v_rcp_f32_e32 v182, v182
	v_rcp_f32_e32 v183, v183
	v_mul_f32_e32 v176, v84, v176
	v_mul_f32_e32 v177, v85, v177
	v_mul_f32_e32 v178, v86, v178
	v_mul_f32_e32 v179, v87, v179
	v_mul_f32_e32 v180, v80, v180
	v_mul_f32_e32 v181, v81, v181
	v_mul_f32_e32 v182, v82, v182
	v_mul_f32_e32 v183, v83, v183
	v_mul_f32_e32 v176, v92, v176
	v_mul_f32_e32 v177, v93, v177
	v_mul_f32_e32 v178, v94, v178
	v_mul_f32_e32 v179, v95, v179
	v_mul_f32_e32 v180, v88, v180
	v_mul_f32_e32 v181, v89, v181
	v_mul_f32_e32 v182, v90, v182
	v_mul_f32_e32 v183, v91, v183
	v_cvt_pk_bf16_f32 v192, v176, v177
	v_cvt_pk_bf16_f32 v193, v178, v179
	v_cvt_pk_bf16_f32 v194, v180, v181
	v_cvt_pk_bf16_f32 v195, v182, v183
	v_add_u32_e32 v200, 0x2c000, v248
	global_store_dwordx4 v200, v[192:195], s[48:49]
	v_pk_mul_f32 v[68:69], v[68:69], v[242:243] op_sel_hi:[1,0]
	v_pk_mul_f32 v[70:71], v[70:71], v[242:243] op_sel_hi:[1,0]
	v_pk_mul_f32 v[64:65], v[64:65], v[242:243] op_sel_hi:[1,0]
	v_pk_mul_f32 v[66:67], v[66:67], v[242:243] op_sel_hi:[1,0]
	v_pk_mul_f32 v[76:77], v[76:77], v[242:243] op_sel_hi:[1,0]
	v_pk_mul_f32 v[78:79], v[78:79], v[242:243] op_sel_hi:[1,0]
	v_pk_mul_f32 v[72:73], v[72:73], v[242:243] op_sel_hi:[1,0]
	v_pk_mul_f32 v[74:75], v[74:75], v[242:243] op_sel_hi:[1,0]
	v_mul_f32_e32 v184, 0xbfb8aa3b, v68
	v_mul_f32_e32 v185, 0xbfb8aa3b, v69
	v_mul_f32_e32 v186, 0xbfb8aa3b, v70
	v_mul_f32_e32 v187, 0xbfb8aa3b, v71
	v_mul_f32_e32 v188, 0xbfb8aa3b, v64
	v_mul_f32_e32 v189, 0xbfb8aa3b, v65
	v_mul_f32_e32 v190, 0xbfb8aa3b, v66
	v_mul_f32_e32 v191, 0xbfb8aa3b, v67
	v_exp_f32_e32 v184, v184
	v_exp_f32_e32 v185, v185
	v_exp_f32_e32 v186, v186
	v_exp_f32_e32 v187, v187
	v_exp_f32_e32 v188, v188
	v_exp_f32_e32 v189, v189
	v_exp_f32_e32 v190, v190
	v_exp_f32_e32 v191, v191
	v_add_f32_e32 v184, 1.0, v184
	v_add_f32_e32 v185, 1.0, v185
	v_add_f32_e32 v186, 1.0, v186
	v_add_f32_e32 v187, 1.0, v187
	v_add_f32_e32 v188, 1.0, v188
	v_add_f32_e32 v189, 1.0, v189
	v_add_f32_e32 v190, 1.0, v190
	v_add_f32_e32 v191, 1.0, v191
	v_rcp_f32_e32 v184, v184
	v_rcp_f32_e32 v185, v185
	v_rcp_f32_e32 v186, v186
	v_rcp_f32_e32 v187, v187
	v_rcp_f32_e32 v188, v188
	v_rcp_f32_e32 v189, v189
	v_rcp_f32_e32 v190, v190
	v_rcp_f32_e32 v191, v191
	v_mul_f32_e32 v184, v68, v184
	v_mul_f32_e32 v185, v69, v185
	v_mul_f32_e32 v186, v70, v186
	v_mul_f32_e32 v187, v71, v187
	v_mul_f32_e32 v188, v64, v188
	v_mul_f32_e32 v189, v65, v189
	v_mul_f32_e32 v190, v66, v190
	v_mul_f32_e32 v191, v67, v191
	v_mul_f32_e32 v184, v76, v184
	v_mul_f32_e32 v185, v77, v185
	v_mul_f32_e32 v186, v78, v186
	v_mul_f32_e32 v187, v79, v187
	v_mul_f32_e32 v188, v72, v188
	v_mul_f32_e32 v189, v73, v189
	v_mul_f32_e32 v190, v74, v190
	v_mul_f32_e32 v191, v75, v191
	v_cvt_pk_bf16_f32 v196, v184, v185
	v_cvt_pk_bf16_f32 v197, v186, v187
	v_cvt_pk_bf16_f32 v198, v188, v189
	v_cvt_pk_bf16_f32 v199, v190, v191
	v_add_u32_e32 v201, 0x42000, v248
	global_store_dwordx4 v201, v[196:199], s[48:49]
	s_waitcnt vmcnt(4)
	v_add_f32_e32 v154, v154, v155
	v_add_f32_e32 v156, v156, v157
	v_add_f32_e32 v158, v158, v159
	v_add_f32_e32 v160, v160, v161
	v_add_f32_e32 v162, v162, v163
	v_add_f32_e32 v164, v164, v165
	v_add_f32_e32 v166, v166, v167
	v_add_f32_e32 v168, v168, v169
	v_add_f32_e32 v154, v154, v156
	v_add_f32_e32 v158, v158, v160
	v_add_f32_e32 v162, v162, v164
	v_add_f32_e32 v166, v166, v168
	ds_bpermute_b32 v155, v171, v154
	ds_bpermute_b32 v159, v171, v158
	ds_bpermute_b32 v163, v171, v162
	ds_bpermute_b32 v167, v171, v166
	s_waitcnt lgkmcnt(0)
;     __device__ __forceinline__ void operator()(const f32x4 (&acc)[2], int srow, int cgp, int kq) const { one(acc[0], srow, 2 * cgp, kq); one(acc[1], srow, 2 * cgp + 1, kq); }
;     __device__ __forceinline__ void operator()(AccRef acc, const pg8::Unit& u, int wr, int wc, int fr, int fq) const {
;         const int row0 = u.pm * 256 + wr * 64 + fr, col0 = u.pn * 128 + wc * 32 + 8 * fq;
; #pragma unroll
;         for (int ai = 0; ai < 2; ++ai)
; #pragma unroll
;             for (int m = 0; m < 4; ++m) {
;                 const int row = row0 + ai * 128 + m * 16;
;                 const float rs = rs_from(ssp + (size_t)row * 16, 4, 1.0f / 1024.0f);
;                 f32x4 o[2];
; #pragma unroll
;                 for (int n = 0; n < 2; ++n)
; #pragma unroll
;                     for (int j = 0; j < 4; ++j) {
;                         const float g = acc[ai][0][m][n][j] * rs, up = acc[ai][1][m][n][j] * rs;
;                         o[n][j] = g * __builtin_amdgcn_rcpf(1.0f + __expf(-g)) * up;
;                     }
;                 *(u32x4*)(act + (size_t)row * FF + col0) = pack8(o[0], o[1]);
;             }
	v_add_f32_e32 v154, v154, v155
	v_add_f32_e32 v158, v158, v159
	v_add_f32_e32 v162, v162, v163
	v_add_f32_e32 v166, v166, v167
	ds_bpermute_b32 v155, v172, v154
	ds_bpermute_b32 v159, v172, v158
	ds_bpermute_b32 v163, v172, v162
	ds_bpermute_b32 v167, v172, v166
	s_waitcnt lgkmcnt(0)
	v_add_f32_e32 v154, v154, v155
	v_add_f32_e32 v158, v158, v159
	v_add_f32_e32 v162, v162, v163
	v_add_f32_e32 v166, v166, v167
	v_fmamk_f32 v154, v154, 0x3a800000, v152
	v_fmamk_f32 v158, v158, 0x3a800000, v152
	v_fmamk_f32 v162, v162, 0x3a800000, v152
	v_fmamk_f32 v166, v166, 0x3a800000, v152
	v_rsq_f32_e32 v154, v154
	v_rsq_f32_e32 v158, v158
	v_rsq_f32_e32 v162, v162
	v_rsq_f32_e32 v166, v166
	s_nop 0
	v_pk_mul_f32 v[52:53], v[52:53], v[154:155] op_sel_hi:[1,0]
	v_pk_mul_f32 v[54:55], v[54:55], v[154:155] op_sel_hi:[1,0]
	v_pk_mul_f32 v[48:49], v[48:49], v[154:155] op_sel_hi:[1,0]
	v_pk_mul_f32 v[50:51], v[50:51], v[154:155] op_sel_hi:[1,0]
	v_pk_mul_f32 v[60:61], v[60:61], v[154:155] op_sel_hi:[1,0]
	v_pk_mul_f32 v[62:63], v[62:63], v[154:155] op_sel_hi:[1,0]
	v_pk_mul_f32 v[56:57], v[56:57], v[154:155] op_sel_hi:[1,0]
	v_pk_mul_f32 v[58:59], v[58:59], v[154:155] op_sel_hi:[1,0]
	v_mul_f32_e32 v176, 0xbfb8aa3b, v52
	v_mul_f32_e32 v177, 0xbfb8aa3b, v53
	v_mul_f32_e32 v178, 0xbfb8aa3b, v54
	v_mul_f32_e32 v179, 0xbfb8aa3b, v55
	v_mul_f32_e32 v180, 0xbfb8aa3b, v48
	v_mul_f32_e32 v181, 0xbfb8aa3b, v49
	v_mul_f32_e32 v182, 0xbfb8aa3b, v50
	v_mul_f32_e32 v183, 0xbfb8aa3b, v51
	v_exp_f32_e32 v176, v176
	v_exp_f32_e32 v177, v177
	v_exp_f32_e32 v178, v178
	v_exp_f32_e32 v179, v179
	v_exp_f32_e32 v180, v180
	v_exp_f32_e32 v181, v181
	v_exp_f32_e32 v182, v182
	v_exp_f32_e32 v183, v183
	v_add_f32_e32 v176, 1.0, v176
	v_add_f32_e32 v177, 1.0, v177
	v_add_f32_e32 v178, 1.0, v178
	v_add_f32_e32 v179, 1.0, v179
	v_add_f32_e32 v180, 1.0, v180
	v_add_f32_e32 v181, 1.0, v181
	v_add_f32_e32 v182, 1.0, v182
	v_add_f32_e32 v183, 1.0, v183
	v_rcp_f32_e32 v176, v176
	v_rcp_f32_e32 v177, v177
	v_rcp_f32_e32 v178, v178
	v_rcp_f32_e32 v179, v179
	v_rcp_f32_e32 v180, v180
	v_rcp_f32_e32 v181, v181
	v_rcp_f32_e32 v182, v182
	v_rcp_f32_e32 v183, v183
	v_mul_f32_e32 v176, v52, v176
	v_mul_f32_e32 v177, v53, v177
	v_mul_f32_e32 v178, v54, v178
	v_mul_f32_e32 v179, v55, v179
	v_mul_f32_e32 v180, v48, v180
	v_mul_f32_e32 v181, v49, v181
	v_mul_f32_e32 v182, v50, v182
	v_mul_f32_e32 v183, v51, v183
	v_mul_f32_e32 v176, v60, v176
	v_mul_f32_e32 v177, v61, v177
	v_mul_f32_e32 v178, v62, v178
	v_mul_f32_e32 v179, v63, v179
	v_mul_f32_e32 v180, v56, v180
	v_mul_f32_e32 v181, v57, v181
	v_mul_f32_e32 v182, v58, v182
	v_mul_f32_e32 v183, v59, v183
	v_cvt_pk_bf16_f32 v192, v176, v177
	v_cvt_pk_bf16_f32 v193, v178, v179
	v_cvt_pk_bf16_f32 v194, v180, v181
	v_cvt_pk_bf16_f32 v195, v182, v183
	v_add_u32_e32 v200, 0xb0000, v248
	global_store_dwordx4 v200, v[192:195], s[48:49]
	v_pk_mul_f32 v[36:37], v[36:37], v[158:159] op_sel_hi:[1,0]
	v_pk_mul_f32 v[38:39], v[38:39], v[158:159] op_sel_hi:[1,0]
	v_pk_mul_f32 v[32:33], v[32:33], v[158:159] op_sel_hi:[1,0]
	v_pk_mul_f32 v[34:35], v[34:35], v[158:159] op_sel_hi:[1,0]
	v_pk_mul_f32 v[44:45], v[44:45], v[158:159] op_sel_hi:[1,0]
	v_pk_mul_f32 v[46:47], v[46:47], v[158:159] op_sel_hi:[1,0]
	v_pk_mul_f32 v[40:41], v[40:41], v[158:159] op_sel_hi:[1,0]
	v_pk_mul_f32 v[42:43], v[42:43], v[158:159] op_sel_hi:[1,0]
	v_mul_f32_e32 v184, 0xbfb8aa3b, v36
	v_mul_f32_e32 v185, 0xbfb8aa3b, v37
	v_mul_f32_e32 v186, 0xbfb8aa3b, v38
	v_mul_f32_e32 v187, 0xbfb8aa3b, v39
	v_mul_f32_e32 v188, 0xbfb8aa3b, v32
	v_mul_f32_e32 v189, 0xbfb8aa3b, v33
	v_mul_f32_e32 v190, 0xbfb8aa3b, v34
	v_mul_f32_e32 v191, 0xbfb8aa3b, v35
	v_exp_f32_e32 v184, v184
	v_exp_f32_e32 v185, v185
	v_exp_f32_e32 v186, v186
	v_exp_f32_e32 v187, v187
	v_exp_f32_e32 v188, v188
	v_exp_f32_e32 v189, v189
	v_exp_f32_e32 v190, v190
	v_exp_f32_e32 v191, v191
	v_add_f32_e32 v184, 1.0, v184
	v_add_f32_e32 v185, 1.0, v185
	v_add_f32_e32 v186, 1.0, v186
	v_add_f32_e32 v187, 1.0, v187
	v_add_f32_e32 v188, 1.0, v188
	v_add_f32_e32 v189, 1.0, v189
	v_add_f32_e32 v190, 1.0, v190
	v_add_f32_e32 v191, 1.0, v191
	v_rcp_f32_e32 v184, v184
	v_rcp_f32_e32 v185, v185
	v_rcp_f32_e32 v186, v186
	v_rcp_f32_e32 v187, v187
	v_rcp_f32_e32 v188, v188
	v_rcp_f32_e32 v189, v189
	v_rcp_f32_e32 v190, v190
	v_rcp_f32_e32 v191, v191
	v_mul_f32_e32 v184, v36, v184
	v_mul_f32_e32 v185, v37, v185
	v_mul_f32_e32 v186, v38, v186
	v_mul_f32_e32 v187, v39, v187
	v_mul_f32_e32 v188, v32, v188
	v_mul_f32_e32 v189, v33, v189
	v_mul_f32_e32 v190, v34, v190
	v_mul_f32_e32 v191, v35, v191
	v_mul_f32_e32 v184, v44, v184
	v_mul_f32_e32 v185, v45, v185
	v_mul_f32_e32 v186, v46, v186
	v_mul_f32_e32 v187, v47, v187
;     __device__ __forceinline__ void operator()(AccRef acc, const pg8::Unit& u, int wr, int wc, int fr, int fq) const {
;     ...
;             for (int m = 0; m < 4; ++m) {
;                 const int row = row0 + ai * 128 + m * 16;
;                 const float rs = rs_from(ssp + (size_t)row * 16, 4, 1.0f / 1024.0f);
;                 f32x4 o[2];
; #pragma unroll
;                 for (int n = 0; n < 2; ++n)
; #pragma unroll
;                     for (int j = 0; j < 4; ++j) {
;                         const float g = acc[ai][0][m][n][j] * rs, up = acc[ai][1][m][n][j] * rs;
;                         o[n][j] = g * __builtin_amdgcn_rcpf(1.0f + __expf(-g)) * up;
;                     }
;                 *(u32x4*)(act + (size_t)row * FF + col0) = pack8(o[0], o[1]);
	v_mul_f32_e32 v188, v40, v188
	v_mul_f32_e32 v189, v41, v189
	v_mul_f32_e32 v190, v42, v190
	v_mul_f32_e32 v191, v43, v191
	v_cvt_pk_bf16_f32 v196, v184, v185
	v_cvt_pk_bf16_f32 v197, v186, v187
	v_cvt_pk_bf16_f32 v198, v188, v189
	v_cvt_pk_bf16_f32 v199, v190, v191
	v_add_u32_e32 v201, 0xc6000, v248
	global_store_dwordx4 v201, v[196:199], s[48:49]
	v_pk_mul_f32 v[20:21], v[20:21], v[162:163] op_sel_hi:[1,0]
	v_pk_mul_f32 v[22:23], v[22:23], v[162:163] op_sel_hi:[1,0]
	v_pk_mul_f32 v[16:17], v[16:17], v[162:163] op_sel_hi:[1,0]
	v_pk_mul_f32 v[18:19], v[18:19], v[162:163] op_sel_hi:[1,0]
	v_pk_mul_f32 v[28:29], v[28:29], v[162:163] op_sel_hi:[1,0]
	v_pk_mul_f32 v[30:31], v[30:31], v[162:163] op_sel_hi:[1,0]
	v_pk_mul_f32 v[24:25], v[24:25], v[162:163] op_sel_hi:[1,0]
	v_pk_mul_f32 v[26:27], v[26:27], v[162:163] op_sel_hi:[1,0]
	v_mul_f32_e32 v176, 0xbfb8aa3b, v20
	v_mul_f32_e32 v177, 0xbfb8aa3b, v21
	v_mul_f32_e32 v178, 0xbfb8aa3b, v22
	v_mul_f32_e32 v179, 0xbfb8aa3b, v23
	v_mul_f32_e32 v180, 0xbfb8aa3b, v16
	v_mul_f32_e32 v181, 0xbfb8aa3b, v17
	v_mul_f32_e32 v182, 0xbfb8aa3b, v18
	v_mul_f32_e32 v183, 0xbfb8aa3b, v19
	v_exp_f32_e32 v176, v176
	v_exp_f32_e32 v177, v177
	v_exp_f32_e32 v178, v178
	v_exp_f32_e32 v179, v179
	v_exp_f32_e32 v180, v180
	v_exp_f32_e32 v181, v181
	v_exp_f32_e32 v182, v182
	v_exp_f32_e32 v183, v183
	v_add_f32_e32 v176, 1.0, v176
	v_add_f32_e32 v177, 1.0, v177
	v_add_f32_e32 v178, 1.0, v178
	v_add_f32_e32 v179, 1.0, v179
	v_add_f32_e32 v180, 1.0, v180
	v_add_f32_e32 v181, 1.0, v181
	v_add_f32_e32 v182, 1.0, v182
	v_add_f32_e32 v183, 1.0, v183
	v_rcp_f32_e32 v176, v176
	v_rcp_f32_e32 v177, v177
	v_rcp_f32_e32 v178, v178
	v_rcp_f32_e32 v179, v179
	v_rcp_f32_e32 v180, v180
	v_rcp_f32_e32 v181, v181
	v_rcp_f32_e32 v182, v182
	v_rcp_f32_e32 v183, v183
	v_mul_f32_e32 v176, v20, v176
	v_mul_f32_e32 v177, v21, v177
	v_mul_f32_e32 v178, v22, v178
	v_mul_f32_e32 v179, v23, v179
	v_mul_f32_e32 v180, v16, v180
	v_mul_f32_e32 v181, v17, v181
	v_mul_f32_e32 v182, v18, v182
	v_mul_f32_e32 v183, v19, v183
	v_mul_f32_e32 v176, v28, v176
	v_mul_f32_e32 v177, v29, v177
	v_mul_f32_e32 v178, v30, v178
	v_mul_f32_e32 v179, v31, v179
	v_mul_f32_e32 v180, v24, v180
	v_mul_f32_e32 v181, v25, v181
	v_mul_f32_e32 v182, v26, v182
	v_mul_f32_e32 v183, v27, v183
	v_cvt_pk_bf16_f32 v192, v176, v177
	v_cvt_pk_bf16_f32 v193, v178, v179
	v_cvt_pk_bf16_f32 v194, v180, v181
	v_cvt_pk_bf16_f32 v195, v182, v183
	v_add_u32_e32 v200, 0xdc000, v248
	global_store_dwordx4 v200, v[192:195], s[48:49]
	v_pk_mul_f32 v[4:5], v[4:5], v[166:167] op_sel_hi:[1,0]
	v_pk_mul_f32 v[6:7], v[6:7], v[166:167] op_sel_hi:[1,0]
	v_pk_mul_f32 v[0:1], v[0:1], v[166:167] op_sel_hi:[1,0]
	v_pk_mul_f32 v[2:3], v[2:3], v[166:167] op_sel_hi:[1,0]
	v_pk_mul_f32 v[12:13], v[12:13], v[166:167] op_sel_hi:[1,0]
	v_pk_mul_f32 v[14:15], v[14:15], v[166:167] op_sel_hi:[1,0]
	v_pk_mul_f32 v[8:9], v[8:9], v[166:167] op_sel_hi:[1,0]
	v_pk_mul_f32 v[10:11], v[10:11], v[166:167] op_sel_hi:[1,0]
	v_mul_f32_e32 v184, 0xbfb8aa3b, v4
	v_mul_f32_e32 v185, 0xbfb8aa3b, v5
	v_mul_f32_e32 v186, 0xbfb8aa3b, v6
	v_mul_f32_e32 v187, 0xbfb8aa3b, v7
	v_mul_f32_e32 v188, 0xbfb8aa3b, v0
	v_mul_f32_e32 v189, 0xbfb8aa3b, v1
	v_mul_f32_e32 v190, 0xbfb8aa3b, v2
	v_mul_f32_e32 v191, 0xbfb8aa3b, v3
	v_exp_f32_e32 v184, v184
	v_exp_f32_e32 v185, v185
	v_exp_f32_e32 v186, v186
	v_exp_f32_e32 v187, v187
	v_exp_f32_e32 v188, v188
	v_exp_f32_e32 v189, v189
	v_exp_f32_e32 v190, v190
	v_exp_f32_e32 v191, v191
	v_add_f32_e32 v184, 1.0, v184
	v_add_f32_e32 v185, 1.0, v185
	v_add_f32_e32 v186, 1.0, v186
	v_add_f32_e32 v187, 1.0, v187
	v_add_f32_e32 v188, 1.0, v188
	v_add_f32_e32 v189, 1.0, v189
	v_add_f32_e32 v190, 1.0, v190
	v_add_f32_e32 v191, 1.0, v191
	v_rcp_f32_e32 v184, v184
	v_rcp_f32_e32 v185, v185
	v_rcp_f32_e32 v186, v186
	v_rcp_f32_e32 v187, v187
	v_rcp_f32_e32 v188, v188
	v_rcp_f32_e32 v189, v189
	v_rcp_f32_e32 v190, v190
	v_rcp_f32_e32 v191, v191
	v_mul_f32_e32 v184, v4, v184
	v_mul_f32_e32 v185, v5, v185
	v_mul_f32_e32 v186, v6, v186
	v_mul_f32_e32 v187, v7, v187
	v_mul_f32_e32 v188, v0, v188
	v_mul_f32_e32 v189, v1, v189
	v_mul_f32_e32 v190, v2, v190
	v_mul_f32_e32 v191, v3, v191
	v_mul_f32_e32 v184, v12, v184
	v_mul_f32_e32 v185, v13, v185
	v_mul_f32_e32 v186, v14, v186
	v_mul_f32_e32 v187, v15, v187
	v_mul_f32_e32 v188, v8, v188
	v_mul_f32_e32 v189, v9, v189
	v_mul_f32_e32 v190, v10, v190
	v_mul_f32_e32 v191, v11, v191
	v_cvt_pk_bf16_f32 v196, v184, v185
	v_cvt_pk_bf16_f32 v197, v186, v187
	v_cvt_pk_bf16_f32 v198, v188, v189
	v_cvt_pk_bf16_f32 v199, v190, v191
	v_add_u32_e32 v201, 0xf2000, v248
	global_store_dwordx4 v201, v[196:199], s[48:49]
